# adds hand-written software-pipelined hyena post-pass tile loop (on top of GEMM ring K-loops and conv d-loop)
# speedup vs baseline: 1.0369x; 1.0056x over previous
; DI int tidx() { return tid512() & 255; }
; DI int vbid() { return 2 * (int)blockIdx.x + vhalf(); }
; DI void hyena_post_tile(const Params& p, int item, char* smem) {
;   const int tid = tidx();
;   const int ct = item & 7, st = (item >> 3) & 63, b = item >> 9;
;   const bf16_t* HY = (const bf16_t*)(p.ws + OFF_HY) + (size_t)b * 4096 * 1536;
;   const bf16_t* yT = (const bf16_t*)(p.hbuf + HB_YT);
;   bf16_t* sT = (bf16_t*)smem;
;   __syncthreads();
; #pragma unroll
;   for (int i = 0; i < 2; ++i) {
;     int row = (tid >> 3) + 32 * i, ck = tid & 7;
;     u32x4 u = ldg16(yT + ((size_t)(ct * 64 + row) * 8 + b) * 4096 + st * 64 + ck * 8);
; #pragma unroll
;     for (int j = 0; j < 8; ++j) { unsigned wv = u[j >> 1]; sT[(ck * 8 + j) * 72 + row] = (bf16_t)((j & 1) ? (wv >> 16) : (wv & 0xffffu)); }
;   }
;   __syncthreads();
; DI void phase12(const Params& p, char* smem) {
;   for (int it = vbid(); it < P12_RET + P12_HY; it += vgrid()) {
;     if (it < P12_RET) retention_out_unit(p, it, smem);
;     else hyena_post_tile(p, it - P12_RET, smem);
;   }
.LBB0_987:
	s_cmpk_gt_i32 s0, 0x3ff
	s_mov_b64 s[2:3], -1
	s_cbranch_scc0 .LBB0_993
	s_cmp_lg_u32 s29, 0x200
	s_cbranch_scc1 .Lpost_fallback
	s_cmp_ge_u32 s0, 0x600
	s_cbranch_scc1 .Lpost_fallback
	s_sub_u32 s1, s0, 0x400
	s_and_b32 s2, s1, 7
	s_lshr_b32 s3, s1, 3
	s_and_b32 s3, s3, 63
	v_readlane_b32 s16, v246, 31
	v_readlane_b32 s17, v246, 32
	v_readlane_b32 s18, v247, 40
	v_readlane_b32 s19, v247, 41
	v_and_b32_e32 v100, 0xff, v196
	v_lshrrev_b32_e32 v101, 3, v100
	v_and_b32_e32 v102, 7, v100
	s_lshl_b32 s4, s2, 6
	v_add_u32_e32 v103, s4, v101
	v_lshlrev_b32_e32 v103, 16, v103
	s_lshl_b32 s5, s3, 7
	v_lshl_add_u32 v104, v102, 4, s5
	v_add_u32_e32 v103, v103, v104
	s_add_u32 s20, s84, 0x2000000
	s_addc_u32 s21, s85, 0
	v_mov_b32_e32 v104, 0
	v_mov_b32_e32 v105, 0
	v_mov_b32_e32 v88, v103
	v_mov_b32_e32 v89, 0
	v_lshl_add_u64 v[88:89], s[20:21], 0, v[88:89]
	s_mov_b32 s22, 0x200000
	s_mov_b32 s23, 0
	v_lshl_add_u64 v[90:91], v[88:89], 0, s[22:23]
	s_lshl_b32 s6, s3, 6
	v_add_u32_e32 v106, s6, v101
	s_movk_i32 s7, 0xc00
	v_mul_lo_u32 v107, v106, s7
	s_lshl_b32 s10, s2, 7
	v_lshl_add_u32 v108, v102, 4, s10
	v_add_u32_e32 v107, v107, v108
	s_add_u32 s20, s16, 0x15af0000
	s_addc_u32 s21, s17, 0
	v_mov_b32_e32 v92, v107
	v_mov_b32_e32 v93, 0
	v_lshl_add_u64 v[92:93], s[20:21], 0, v[92:93]
	s_mov_b32 s22, 0x18000
	v_lshl_add_u64 v[94:95], v[92:93], 0, s[22:23]
	v_lshlrev_b32_e32 v109, 11, v106
	v_add_u32_e32 v109, v109, v108
	v_add_u32_e32 v109, 0x400, v109
	s_add_u32 s20, s16, 0x7af0000
	s_addc_u32 s21, s17, 0
	v_mov_b32_e32 v96, v109
	v_mov_b32_e32 v97, 0
	v_lshl_add_u64 v[96:97], s[20:21], 0, v[96:97]
	s_mov_b32 s22, 0x10000
	v_lshl_add_u64 v[98:99], v[96:97], 0, s[22:23]
	v_lshlrev_b32_e32 v110, 1, v108
	v_mov_b32_e32 v111, 0
	v_lshl_add_u64 v[110:111], s[18:19], 0, v[110:111]
	s_mov_b32 s22, 0x1800
	v_lshl_add_u64 v[112:113], v[110:111], 0, s[22:23]
	v_lshl_add_u64 v[114:115], v[112:113], 0, s[22:23]
	global_load_dwordx4 v[64:67], v[110:111], off
	global_load_dwordx4 v[68:71], v[110:111], off offset:16
	global_load_dwordx4 v[72:75], v[112:113], off
	global_load_dwordx4 v[76:79], v[112:113], off offset:16
	global_load_dwordx4 v[80:83], v[114:115], off
	global_load_dwordx4 v[84:87], v[114:115], off offset:16
	v_cmp_ne_u32_e64 s[40:41], 0, v106
	v_add_u32_e32 v116, 32, v106
	s_movk_i32 s7, 0xfff
	v_cmp_ne_u32_e64 s[42:43], s7, v116
	v_mul_u32_u24_e32 v117, 0x480, v102
	v_lshl_add_u32 v117, v101, 1, v117
	v_add_u32_e32 v117, s24, v117
	v_mul_u32_u24_e32 v118, 0x90, v101
	v_lshl_add_u32 v118, v102, 4, v118
	v_add_u32_e32 v118, s24, v118
	s_mov_b32 s44, 0x2000
	s_mov_b32 s45, 0
	s_mov_b32 s46, 0xc00000
	s_mov_b32 s47, 0
	s_mov_b32 s48, 0x800000
	s_mov_b32 s49, 0
	global_load_dwordx4 v[0:3], v[88:89], off
	global_load_dwordx4 v[4:7], v[90:91], off
	global_load_dwordx4 v[8:11], v[92:93], off offset:-3072
	global_load_dwordx4 v[12:15], v[92:93], off offset:0
	global_load_dwordx4 v[16:19], v[92:93], off offset:3072
	global_load_dwordx4 v[20:23], v[94:95], off offset:-3072
	global_load_dwordx4 v[24:27], v[94:95], off offset:0
	global_load_dwordx4 v[28:31], v[94:95], off offset:3072
	v_lshl_add_u64 v[88:89], v[88:89], 0, s[44:45]
	v_lshl_add_u64 v[90:91], v[90:91], 0, s[44:45]
	v_lshl_add_u64 v[92:93], v[92:93], 0, s[46:47]
	v_lshl_add_u64 v[94:95], v[94:95], 0, s[46:47]
	s_barrier
	global_load_dwordx4 v[32:35], v[88:89], off
	global_load_dwordx4 v[36:39], v[90:91], off
	global_load_dwordx4 v[40:43], v[92:93], off offset:-3072
	global_load_dwordx4 v[44:47], v[92:93], off offset:0
	global_load_dwordx4 v[48:51], v[92:93], off offset:3072
	global_load_dwordx4 v[52:55], v[94:95], off offset:-3072
	global_load_dwordx4 v[56:59], v[94:95], off offset:0
	global_load_dwordx4 v[60:63], v[94:95], off offset:3072
	v_lshl_add_u64 v[88:89], v[88:89], 0, s[44:45]
	v_lshl_add_u64 v[90:91], v[90:91], 0, s[44:45]
	v_lshl_add_u64 v[92:93], v[92:93], 0, s[46:47]
	v_lshl_add_u64 v[94:95], v[94:95], 0, s[46:47]
	s_waitcnt vmcnt(8)
	ds_write_b16 v117, v0
	ds_write_b16_d16_hi v117, v0 offset:144
	ds_write_b16 v117, v1 offset:288
	ds_write_b16_d16_hi v117, v1 offset:432
	ds_write_b16 v117, v2 offset:576
	ds_write_b16_d16_hi v117, v2 offset:720
	ds_write_b16 v117, v3 offset:864
	ds_write_b16_d16_hi v117, v3 offset:1008
	ds_write_b16 v117, v4 offset:64
	ds_write_b16_d16_hi v117, v4 offset:208
	ds_write_b16 v117, v5 offset:352
	ds_write_b16_d16_hi v117, v5 offset:496
	ds_write_b16 v117, v6 offset:640
	ds_write_b16_d16_hi v117, v6 offset:784
	ds_write_b16 v117, v7 offset:928
	ds_write_b16_d16_hi v117, v7 offset:1072
	s_waitcnt lgkmcnt(0)
	s_barrier
; DI float bflo(unsigned u) { return __uint_as_float(u << 16); }
; DI float bfhi(unsigned u) { return __uint_as_float(u & 0xffff0000u); }
; DI void hyena_post_tile(const Params& p, int item, char* smem) {
;     ...
; #pragma unroll
;   for (int i = 0; i < 2; ++i) {
;     int row = (tid >> 3) + 32 * i, ck = tid & 7;
;     u32x4 u = ldg16(yT + ((size_t)(ct * 64 + row) * 8 + b) * 4096 + st * 64 + ck * 8);
; #pragma unroll
;     for (int j = 0; j < 8; ++j) { unsigned wv = u[j >> 1]; sT[(ck * 8 + j) * 72 + row] = (bf16_t)((j & 1) ? (wv >> 16) : (wv & 0xffffu)); }
;   }
;     ...
;   bf16_t* CD = (bf16_t*)(p.ws + OFF_AB);
; #pragma unroll
;   for (int i = 0; i < 2; ++i) {
;     int row = (tid >> 3) + 32 * i, ck = tid & 7, s = st * 64 + row, c = ct * 64 + ck * 8;
;     float x0[8];
; #pragma unroll
;     for (int j = 0; j < 8; ++j) x0[j] = 0.f;
; #pragma unroll
;     for (int d = -1; d <= 1; ++d) {
;       int ss = s + d;
;       if (ss >= 0 && ss < 4096) {
;         u32x4 a = ldg16(HY + (size_t)ss * 1536 + c);
;         float wa[8]; ld8f(p.c_short + (d + 1) * 1536 + c, wa);
; #pragma unroll
;         for (int q = 0; q < 4; ++q) { x0[2 * q] += wa[2 * q] * bflo(a[q]); x0[2 * q + 1] += wa[2 * q + 1] * bfhi(a[q]); }
;       }
;     }
;     u32x4 y = *(const u32x4*)(sT + row * 72 + ck * 8);
;     float v[8];
; #pragma unroll
;     for (int q = 0; q < 4; ++q) { v[2 * q] = bflo(y[q]) * x0[2 * q]; v[2 * q + 1] = bfhi(y[q]) * x0[2 * q + 1]; }
;     store8(CD + ((size_t)b * 4096 + s) * 1024 + 512 + c, v);
;   }
	ds_read_b128 v[120:123], v118
	ds_read_b128 v[124:127], v118 offset:4608
	v_cndmask_b32_e64 v8, 0, v8, s[40:41]
	v_cndmask_b32_e64 v9, 0, v9, s[40:41]
	v_cndmask_b32_e64 v10, 0, v10, s[40:41]
	v_cndmask_b32_e64 v11, 0, v11, s[40:41]
	s_waitcnt lgkmcnt(1)
	v_lshlrev_b32_e32 v128, 16, v8
	v_and_b32_e32 v129, 0xffff0000, v8
	v_lshlrev_b32_e32 v130, 16, v12
	v_and_b32_e32 v131, 0xffff0000, v12
	v_lshlrev_b32_e32 v132, 16, v16
	v_and_b32_e32 v133, 0xffff0000, v16
	v_lshlrev_b32_e32 v134, 16, v120
	v_and_b32_e32 v135, 0xffff0000, v120
	v_pk_fma_f32 v[136:137], v[64:65], v[128:129], 0 op_sel_hi:[1,1,0]
	v_pk_fma_f32 v[136:137], v[72:73], v[130:131], v[136:137]
	v_pk_fma_f32 v[136:137], v[80:81], v[132:133], v[136:137]
	v_pk_mul_f32 v[136:137], v[134:135], v[136:137]
	v_cvt_pk_bf16_f32 v140, v136, v137
	v_lshlrev_b32_e32 v128, 16, v9
	v_and_b32_e32 v129, 0xffff0000, v9
	v_lshlrev_b32_e32 v130, 16, v13
	v_and_b32_e32 v131, 0xffff0000, v13
	v_lshlrev_b32_e32 v132, 16, v17
	v_and_b32_e32 v133, 0xffff0000, v17
	v_lshlrev_b32_e32 v134, 16, v121
	v_and_b32_e32 v135, 0xffff0000, v121
	v_pk_fma_f32 v[136:137], v[66:67], v[128:129], 0 op_sel_hi:[1,1,0]
	v_pk_fma_f32 v[136:137], v[74:75], v[130:131], v[136:137]
	v_pk_fma_f32 v[136:137], v[82:83], v[132:133], v[136:137]
	v_pk_mul_f32 v[136:137], v[134:135], v[136:137]
	v_cvt_pk_bf16_f32 v141, v136, v137
	v_lshlrev_b32_e32 v128, 16, v10
	v_and_b32_e32 v129, 0xffff0000, v10
	v_lshlrev_b32_e32 v130, 16, v14
	v_and_b32_e32 v131, 0xffff0000, v14
	v_lshlrev_b32_e32 v132, 16, v18
	v_and_b32_e32 v133, 0xffff0000, v18
	v_lshlrev_b32_e32 v134, 16, v122
	v_and_b32_e32 v135, 0xffff0000, v122
	v_pk_fma_f32 v[136:137], v[68:69], v[128:129], 0 op_sel_hi:[1,1,0]
	v_pk_fma_f32 v[136:137], v[76:77], v[130:131], v[136:137]
	v_pk_fma_f32 v[136:137], v[84:85], v[132:133], v[136:137]
	v_pk_mul_f32 v[136:137], v[134:135], v[136:137]
	v_cvt_pk_bf16_f32 v142, v136, v137
	v_lshlrev_b32_e32 v128, 16, v11
	v_and_b32_e32 v129, 0xffff0000, v11
	v_lshlrev_b32_e32 v130, 16, v15
	v_and_b32_e32 v131, 0xffff0000, v15
	v_lshlrev_b32_e32 v132, 16, v19
	v_and_b32_e32 v133, 0xffff0000, v19
	v_lshlrev_b32_e32 v134, 16, v123
	v_and_b32_e32 v135, 0xffff0000, v123
	v_pk_fma_f32 v[136:137], v[70:71], v[128:129], 0 op_sel_hi:[1,1,0]
	v_pk_fma_f32 v[136:137], v[78:79], v[130:131], v[136:137]
	v_pk_fma_f32 v[136:137], v[86:87], v[132:133], v[136:137]
	v_pk_mul_f32 v[136:137], v[134:135], v[136:137]
	v_cvt_pk_bf16_f32 v143, v136, v137
	global_store_dwordx4 v[96:97], v[140:143], off
	v_cndmask_b32_e64 v28, 0, v28, s[42:43]
	v_cndmask_b32_e64 v29, 0, v29, s[42:43]
	v_cndmask_b32_e64 v30, 0, v30, s[42:43]
	v_cndmask_b32_e64 v31, 0, v31, s[42:43]
	s_waitcnt lgkmcnt(0)
	v_lshlrev_b32_e32 v128, 16, v20
	v_and_b32_e32 v129, 0xffff0000, v20
	v_lshlrev_b32_e32 v130, 16, v24
	v_and_b32_e32 v131, 0xffff0000, v24
	v_lshlrev_b32_e32 v132, 16, v28
	v_and_b32_e32 v133, 0xffff0000, v28
	v_lshlrev_b32_e32 v134, 16, v124
	v_and_b32_e32 v135, 0xffff0000, v124
	v_pk_fma_f32 v[136:137], v[64:65], v[128:129], 0 op_sel_hi:[1,1,0]
	v_pk_fma_f32 v[136:137], v[72:73], v[130:131], v[136:137]
	v_pk_fma_f32 v[136:137], v[80:81], v[132:133], v[136:137]
	v_pk_mul_f32 v[136:137], v[134:135], v[136:137]
	v_cvt_pk_bf16_f32 v144, v136, v137
	v_lshlrev_b32_e32 v128, 16, v21
	v_and_b32_e32 v129, 0xffff0000, v21
	v_lshlrev_b32_e32 v130, 16, v25
	v_and_b32_e32 v131, 0xffff0000, v25
	v_lshlrev_b32_e32 v132, 16, v29
	v_and_b32_e32 v133, 0xffff0000, v29
	v_lshlrev_b32_e32 v134, 16, v125
	v_and_b32_e32 v135, 0xffff0000, v125
	v_pk_fma_f32 v[136:137], v[66:67], v[128:129], 0 op_sel_hi:[1,1,0]
	v_pk_fma_f32 v[136:137], v[74:75], v[130:131], v[136:137]
	v_pk_fma_f32 v[136:137], v[82:83], v[132:133], v[136:137]
	v_pk_mul_f32 v[136:137], v[134:135], v[136:137]
	v_cvt_pk_bf16_f32 v145, v136, v137
	v_lshlrev_b32_e32 v128, 16, v22
	v_and_b32_e32 v129, 0xffff0000, v22
	v_lshlrev_b32_e32 v130, 16, v26
	v_and_b32_e32 v131, 0xffff0000, v26
	v_lshlrev_b32_e32 v132, 16, v30
	v_and_b32_e32 v133, 0xffff0000, v30
	v_lshlrev_b32_e32 v134, 16, v126
	v_and_b32_e32 v135, 0xffff0000, v126
	v_pk_fma_f32 v[136:137], v[68:69], v[128:129], 0 op_sel_hi:[1,1,0]
	v_pk_fma_f32 v[136:137], v[76:77], v[130:131], v[136:137]
	v_pk_fma_f32 v[136:137], v[84:85], v[132:133], v[136:137]
	v_pk_mul_f32 v[136:137], v[134:135], v[136:137]
	v_cvt_pk_bf16_f32 v146, v136, v137
	v_lshlrev_b32_e32 v128, 16, v23
	v_and_b32_e32 v129, 0xffff0000, v23
	v_lshlrev_b32_e32 v130, 16, v27
	v_and_b32_e32 v131, 0xffff0000, v27
	v_lshlrev_b32_e32 v132, 16, v31
	v_and_b32_e32 v133, 0xffff0000, v31
	v_lshlrev_b32_e32 v134, 16, v127
	v_and_b32_e32 v135, 0xffff0000, v127
	v_pk_fma_f32 v[136:137], v[70:71], v[128:129], 0 op_sel_hi:[1,1,0]
	v_pk_fma_f32 v[136:137], v[78:79], v[130:131], v[136:137]
	v_pk_fma_f32 v[136:137], v[86:87], v[132:133], v[136:137]
	v_pk_mul_f32 v[136:137], v[134:135], v[136:137]
	v_cvt_pk_bf16_f32 v147, v136, v137
	global_store_dwordx4 v[98:99], v[144:147], off
	v_lshl_add_u64 v[96:97], v[96:97], 0, s[48:49]
	v_lshl_add_u64 v[98:99], v[98:99], 0, s[48:49]
	global_load_dwordx4 v[0:3], v[88:89], off
	global_load_dwordx4 v[4:7], v[90:91], off
	global_load_dwordx4 v[8:11], v[92:93], off offset:-3072
	global_load_dwordx4 v[12:15], v[92:93], off offset:0
	global_load_dwordx4 v[16:19], v[92:93], off offset:3072
	global_load_dwordx4 v[20:23], v[94:95], off offset:-3072
	global_load_dwordx4 v[24:27], v[94:95], off offset:0
	global_load_dwordx4 v[28:31], v[94:95], off offset:3072
	v_lshl_add_u64 v[88:89], v[88:89], 0, s[44:45]
	v_lshl_add_u64 v[90:91], v[90:91], 0, s[44:45]
	v_lshl_add_u64 v[92:93], v[92:93], 0, s[46:47]
	v_lshl_add_u64 v[94:95], v[94:95], 0, s[46:47]
	s_waitcnt vmcnt(10)
	ds_write_b16 v117, v32 offset:9216
	ds_write_b16_d16_hi v117, v32 offset:9360
	ds_write_b16 v117, v33 offset:9504
	ds_write_b16_d16_hi v117, v33 offset:9648
	ds_write_b16 v117, v34 offset:9792
	ds_write_b16_d16_hi v117, v34 offset:9936
	ds_write_b16 v117, v35 offset:10080
	ds_write_b16_d16_hi v117, v35 offset:10224
	ds_write_b16 v117, v36 offset:9280
	ds_write_b16_d16_hi v117, v36 offset:9424
	ds_write_b16 v117, v37 offset:9568
	ds_write_b16_d16_hi v117, v37 offset:9712
	ds_write_b16 v117, v38 offset:9856
	ds_write_b16_d16_hi v117, v38 offset:10000
	ds_write_b16 v117, v39 offset:10144
	ds_write_b16_d16_hi v117, v39 offset:10288
	s_waitcnt lgkmcnt(0)
	s_barrier
; DI float bflo(unsigned u) { return __uint_as_float(u << 16); }
; DI float bfhi(unsigned u) { return __uint_as_float(u & 0xffff0000u); }
; DI void hyena_post_tile(const Params& p, int item, char* smem) {
;     ...
; #pragma unroll
;   for (int i = 0; i < 2; ++i) {
;     int row = (tid >> 3) + 32 * i, ck = tid & 7;
;     u32x4 u = ldg16(yT + ((size_t)(ct * 64 + row) * 8 + b) * 4096 + st * 64 + ck * 8);
; #pragma unroll
;     for (int j = 0; j < 8; ++j) { unsigned wv = u[j >> 1]; sT[(ck * 8 + j) * 72 + row] = (bf16_t)((j & 1) ? (wv >> 16) : (wv & 0xffffu)); }
;   }
;     ...
;   bf16_t* CD = (bf16_t*)(p.ws + OFF_AB);
; #pragma unroll
;   for (int i = 0; i < 2; ++i) {
;     int row = (tid >> 3) + 32 * i, ck = tid & 7, s = st * 64 + row, c = ct * 64 + ck * 8;
;     float x0[8];
; #pragma unroll
;     for (int j = 0; j < 8; ++j) x0[j] = 0.f;
; #pragma unroll
;     for (int d = -1; d <= 1; ++d) {
;       int ss = s + d;
;       if (ss >= 0 && ss < 4096) {
;         u32x4 a = ldg16(HY + (size_t)ss * 1536 + c);
;         float wa[8]; ld8f(p.c_short + (d + 1) * 1536 + c, wa);
; #pragma unroll
;         for (int q = 0; q < 4; ++q) { x0[2 * q] += wa[2 * q] * bflo(a[q]); x0[2 * q + 1] += wa[2 * q + 1] * bfhi(a[q]); }
;       }
;     }
;     u32x4 y = *(const u32x4*)(sT + row * 72 + ck * 8);
;     float v[8];
; #pragma unroll
;     for (int q = 0; q < 4; ++q) { v[2 * q] = bflo(y[q]) * x0[2 * q]; v[2 * q + 1] = bfhi(y[q]) * x0[2 * q + 1]; }
;     store8(CD + ((size_t)b * 4096 + s) * 1024 + 512 + c, v);
;   }
	ds_read_b128 v[120:123], v118 offset:9216
	ds_read_b128 v[124:127], v118 offset:13824
	v_cndmask_b32_e64 v40, 0, v40, s[40:41]
	v_cndmask_b32_e64 v41, 0, v41, s[40:41]
	v_cndmask_b32_e64 v42, 0, v42, s[40:41]
	v_cndmask_b32_e64 v43, 0, v43, s[40:41]
	s_waitcnt lgkmcnt(1)
	v_lshlrev_b32_e32 v128, 16, v40
	v_and_b32_e32 v129, 0xffff0000, v40
	v_lshlrev_b32_e32 v130, 16, v44
	v_and_b32_e32 v131, 0xffff0000, v44
	v_lshlrev_b32_e32 v132, 16, v48
	v_and_b32_e32 v133, 0xffff0000, v48
	v_lshlrev_b32_e32 v134, 16, v120
	v_and_b32_e32 v135, 0xffff0000, v120
	v_pk_fma_f32 v[136:137], v[64:65], v[128:129], 0 op_sel_hi:[1,1,0]
	v_pk_fma_f32 v[136:137], v[72:73], v[130:131], v[136:137]
	v_pk_fma_f32 v[136:137], v[80:81], v[132:133], v[136:137]
	v_pk_mul_f32 v[136:137], v[134:135], v[136:137]
	v_cvt_pk_bf16_f32 v140, v136, v137
	v_lshlrev_b32_e32 v128, 16, v41
	v_and_b32_e32 v129, 0xffff0000, v41
	v_lshlrev_b32_e32 v130, 16, v45
	v_and_b32_e32 v131, 0xffff0000, v45
	v_lshlrev_b32_e32 v132, 16, v49
	v_and_b32_e32 v133, 0xffff0000, v49
	v_lshlrev_b32_e32 v134, 16, v121
	v_and_b32_e32 v135, 0xffff0000, v121
	v_pk_fma_f32 v[136:137], v[66:67], v[128:129], 0 op_sel_hi:[1,1,0]
	v_pk_fma_f32 v[136:137], v[74:75], v[130:131], v[136:137]
	v_pk_fma_f32 v[136:137], v[82:83], v[132:133], v[136:137]
	v_pk_mul_f32 v[136:137], v[134:135], v[136:137]
	v_cvt_pk_bf16_f32 v141, v136, v137
	v_lshlrev_b32_e32 v128, 16, v42
	v_and_b32_e32 v129, 0xffff0000, v42
	v_lshlrev_b32_e32 v130, 16, v46
	v_and_b32_e32 v131, 0xffff0000, v46
	v_lshlrev_b32_e32 v132, 16, v50
	v_and_b32_e32 v133, 0xffff0000, v50
	v_lshlrev_b32_e32 v134, 16, v122
	v_and_b32_e32 v135, 0xffff0000, v122
	v_pk_fma_f32 v[136:137], v[68:69], v[128:129], 0 op_sel_hi:[1,1,0]
	v_pk_fma_f32 v[136:137], v[76:77], v[130:131], v[136:137]
	v_pk_fma_f32 v[136:137], v[84:85], v[132:133], v[136:137]
	v_pk_mul_f32 v[136:137], v[134:135], v[136:137]
	v_cvt_pk_bf16_f32 v142, v136, v137
	v_lshlrev_b32_e32 v128, 16, v43
	v_and_b32_e32 v129, 0xffff0000, v43
	v_lshlrev_b32_e32 v130, 16, v47
	v_and_b32_e32 v131, 0xffff0000, v47
	v_lshlrev_b32_e32 v132, 16, v51
	v_and_b32_e32 v133, 0xffff0000, v51
	v_lshlrev_b32_e32 v134, 16, v123
	v_and_b32_e32 v135, 0xffff0000, v123
	v_pk_fma_f32 v[136:137], v[70:71], v[128:129], 0 op_sel_hi:[1,1,0]
	v_pk_fma_f32 v[136:137], v[78:79], v[130:131], v[136:137]
	v_pk_fma_f32 v[136:137], v[86:87], v[132:133], v[136:137]
	v_pk_mul_f32 v[136:137], v[134:135], v[136:137]
	v_cvt_pk_bf16_f32 v143, v136, v137
	global_store_dwordx4 v[96:97], v[140:143], off
	v_cndmask_b32_e64 v60, 0, v60, s[42:43]
	v_cndmask_b32_e64 v61, 0, v61, s[42:43]
	v_cndmask_b32_e64 v62, 0, v62, s[42:43]
	v_cndmask_b32_e64 v63, 0, v63, s[42:43]
	s_waitcnt lgkmcnt(0)
	v_lshlrev_b32_e32 v128, 16, v52
	v_and_b32_e32 v129, 0xffff0000, v52
	v_lshlrev_b32_e32 v130, 16, v56
	v_and_b32_e32 v131, 0xffff0000, v56
	v_lshlrev_b32_e32 v132, 16, v60
	v_and_b32_e32 v133, 0xffff0000, v60
	v_lshlrev_b32_e32 v134, 16, v124
	v_and_b32_e32 v135, 0xffff0000, v124
	v_pk_fma_f32 v[136:137], v[64:65], v[128:129], 0 op_sel_hi:[1,1,0]
	v_pk_fma_f32 v[136:137], v[72:73], v[130:131], v[136:137]
	v_pk_fma_f32 v[136:137], v[80:81], v[132:133], v[136:137]
	v_pk_mul_f32 v[136:137], v[134:135], v[136:137]
	v_cvt_pk_bf16_f32 v144, v136, v137
	v_lshlrev_b32_e32 v128, 16, v53
	v_and_b32_e32 v129, 0xffff0000, v53
	v_lshlrev_b32_e32 v130, 16, v57
	v_and_b32_e32 v131, 0xffff0000, v57
	v_lshlrev_b32_e32 v132, 16, v61
	v_and_b32_e32 v133, 0xffff0000, v61
	v_lshlrev_b32_e32 v134, 16, v125
	v_and_b32_e32 v135, 0xffff0000, v125
	v_pk_fma_f32 v[136:137], v[66:67], v[128:129], 0 op_sel_hi:[1,1,0]
	v_pk_fma_f32 v[136:137], v[74:75], v[130:131], v[136:137]
	v_pk_fma_f32 v[136:137], v[82:83], v[132:133], v[136:137]
	v_pk_mul_f32 v[136:137], v[134:135], v[136:137]
	v_cvt_pk_bf16_f32 v145, v136, v137
	v_lshlrev_b32_e32 v128, 16, v54
	v_and_b32_e32 v129, 0xffff0000, v54
	v_lshlrev_b32_e32 v130, 16, v58
	v_and_b32_e32 v131, 0xffff0000, v58
	v_lshlrev_b32_e32 v132, 16, v62
	v_and_b32_e32 v133, 0xffff0000, v62
	v_lshlrev_b32_e32 v134, 16, v126
	v_and_b32_e32 v135, 0xffff0000, v126
	v_pk_fma_f32 v[136:137], v[68:69], v[128:129], 0 op_sel_hi:[1,1,0]
	v_pk_fma_f32 v[136:137], v[76:77], v[130:131], v[136:137]
	v_pk_fma_f32 v[136:137], v[84:85], v[132:133], v[136:137]
	v_pk_mul_f32 v[136:137], v[134:135], v[136:137]
	v_cvt_pk_bf16_f32 v146, v136, v137
	v_lshlrev_b32_e32 v128, 16, v55
	v_and_b32_e32 v129, 0xffff0000, v55
	v_lshlrev_b32_e32 v130, 16, v59
	v_and_b32_e32 v131, 0xffff0000, v59
	v_lshlrev_b32_e32 v132, 16, v63
	v_and_b32_e32 v133, 0xffff0000, v63
	v_lshlrev_b32_e32 v134, 16, v127
	v_and_b32_e32 v135, 0xffff0000, v127
	v_pk_fma_f32 v[136:137], v[70:71], v[128:129], 0 op_sel_hi:[1,1,0]
	v_pk_fma_f32 v[136:137], v[78:79], v[130:131], v[136:137]
	v_pk_fma_f32 v[136:137], v[86:87], v[132:133], v[136:137]
	v_pk_mul_f32 v[136:137], v[134:135], v[136:137]
	v_cvt_pk_bf16_f32 v147, v136, v137
	global_store_dwordx4 v[98:99], v[144:147], off
	v_lshl_add_u64 v[96:97], v[96:97], 0, s[48:49]
	v_lshl_add_u64 v[98:99], v[98:99], 0, s[48:49]
	global_load_dwordx4 v[32:35], v[88:89], off
	global_load_dwordx4 v[36:39], v[90:91], off
	global_load_dwordx4 v[40:43], v[92:93], off offset:-3072
	global_load_dwordx4 v[44:47], v[92:93], off offset:0
	global_load_dwordx4 v[48:51], v[92:93], off offset:3072
	global_load_dwordx4 v[52:55], v[94:95], off offset:-3072
	global_load_dwordx4 v[56:59], v[94:95], off offset:0
	global_load_dwordx4 v[60:63], v[94:95], off offset:3072
	v_lshl_add_u64 v[88:89], v[88:89], 0, s[44:45]
	v_lshl_add_u64 v[90:91], v[90:91], 0, s[44:45]
	v_lshl_add_u64 v[92:93], v[92:93], 0, s[46:47]
	v_lshl_add_u64 v[94:95], v[94:95], 0, s[46:47]
	s_waitcnt vmcnt(10)
	ds_write_b16 v117, v0
	ds_write_b16_d16_hi v117, v0 offset:144
	ds_write_b16 v117, v1 offset:288
	ds_write_b16_d16_hi v117, v1 offset:432
	ds_write_b16 v117, v2 offset:576
	ds_write_b16_d16_hi v117, v2 offset:720
	ds_write_b16 v117, v3 offset:864
	ds_write_b16_d16_hi v117, v3 offset:1008
	ds_write_b16 v117, v4 offset:64
	ds_write_b16_d16_hi v117, v4 offset:208
	ds_write_b16 v117, v5 offset:352
	ds_write_b16_d16_hi v117, v5 offset:496
	ds_write_b16 v117, v6 offset:640
	ds_write_b16_d16_hi v117, v6 offset:784
	ds_write_b16 v117, v7 offset:928
	ds_write_b16_d16_hi v117, v7 offset:1072
	s_waitcnt lgkmcnt(0)
	s_barrier
; DI float bflo(unsigned u) { return __uint_as_float(u << 16); }
; DI float bfhi(unsigned u) { return __uint_as_float(u & 0xffff0000u); }
; DI void hyena_post_tile(const Params& p, int item, char* smem) {
;     ...
; #pragma unroll
;   for (int i = 0; i < 2; ++i) {
;     int row = (tid >> 3) + 32 * i, ck = tid & 7;
;     u32x4 u = ldg16(yT + ((size_t)(ct * 64 + row) * 8 + b) * 4096 + st * 64 + ck * 8);
; #pragma unroll
;     for (int j = 0; j < 8; ++j) { unsigned wv = u[j >> 1]; sT[(ck * 8 + j) * 72 + row] = (bf16_t)((j & 1) ? (wv >> 16) : (wv & 0xffffu)); }
;   }
;     ...
;   bf16_t* CD = (bf16_t*)(p.ws + OFF_AB);
; #pragma unroll
;   for (int i = 0; i < 2; ++i) {
;     int row = (tid >> 3) + 32 * i, ck = tid & 7, s = st * 64 + row, c = ct * 64 + ck * 8;
;     float x0[8];
; #pragma unroll
;     for (int j = 0; j < 8; ++j) x0[j] = 0.f;
; #pragma unroll
;     for (int d = -1; d <= 1; ++d) {
;       int ss = s + d;
;       if (ss >= 0 && ss < 4096) {
;         u32x4 a = ldg16(HY + (size_t)ss * 1536 + c);
;         float wa[8]; ld8f(p.c_short + (d + 1) * 1536 + c, wa);
; #pragma unroll
;         for (int q = 0; q < 4; ++q) { x0[2 * q] += wa[2 * q] * bflo(a[q]); x0[2 * q + 1] += wa[2 * q + 1] * bfhi(a[q]); }
;       }
;     }
;     u32x4 y = *(const u32x4*)(sT + row * 72 + ck * 8);
;     float v[8];
; #pragma unroll
;     for (int q = 0; q < 4; ++q) { v[2 * q] = bflo(y[q]) * x0[2 * q]; v[2 * q + 1] = bfhi(y[q]) * x0[2 * q + 1]; }
;     store8(CD + ((size_t)b * 4096 + s) * 1024 + 512 + c, v);
;   }
	ds_read_b128 v[120:123], v118
	ds_read_b128 v[124:127], v118 offset:4608
	v_cndmask_b32_e64 v8, 0, v8, s[40:41]
	v_cndmask_b32_e64 v9, 0, v9, s[40:41]
	v_cndmask_b32_e64 v10, 0, v10, s[40:41]
	v_cndmask_b32_e64 v11, 0, v11, s[40:41]
	s_waitcnt lgkmcnt(1)
	v_lshlrev_b32_e32 v128, 16, v8
	v_and_b32_e32 v129, 0xffff0000, v8
	v_lshlrev_b32_e32 v130, 16, v12
	v_and_b32_e32 v131, 0xffff0000, v12
	v_lshlrev_b32_e32 v132, 16, v16
	v_and_b32_e32 v133, 0xffff0000, v16
	v_lshlrev_b32_e32 v134, 16, v120
	v_and_b32_e32 v135, 0xffff0000, v120
	v_pk_fma_f32 v[136:137], v[64:65], v[128:129], 0 op_sel_hi:[1,1,0]
	v_pk_fma_f32 v[136:137], v[72:73], v[130:131], v[136:137]
	v_pk_fma_f32 v[136:137], v[80:81], v[132:133], v[136:137]
	v_pk_mul_f32 v[136:137], v[134:135], v[136:137]
	v_cvt_pk_bf16_f32 v140, v136, v137
	v_lshlrev_b32_e32 v128, 16, v9
	v_and_b32_e32 v129, 0xffff0000, v9
	v_lshlrev_b32_e32 v130, 16, v13
	v_and_b32_e32 v131, 0xffff0000, v13
	v_lshlrev_b32_e32 v132, 16, v17
	v_and_b32_e32 v133, 0xffff0000, v17
	v_lshlrev_b32_e32 v134, 16, v121
	v_and_b32_e32 v135, 0xffff0000, v121
	v_pk_fma_f32 v[136:137], v[66:67], v[128:129], 0 op_sel_hi:[1,1,0]
	v_pk_fma_f32 v[136:137], v[74:75], v[130:131], v[136:137]
	v_pk_fma_f32 v[136:137], v[82:83], v[132:133], v[136:137]
	v_pk_mul_f32 v[136:137], v[134:135], v[136:137]
	v_cvt_pk_bf16_f32 v141, v136, v137
	v_lshlrev_b32_e32 v128, 16, v10
	v_and_b32_e32 v129, 0xffff0000, v10
	v_lshlrev_b32_e32 v130, 16, v14
	v_and_b32_e32 v131, 0xffff0000, v14
	v_lshlrev_b32_e32 v132, 16, v18
	v_and_b32_e32 v133, 0xffff0000, v18
	v_lshlrev_b32_e32 v134, 16, v122
	v_and_b32_e32 v135, 0xffff0000, v122
	v_pk_fma_f32 v[136:137], v[68:69], v[128:129], 0 op_sel_hi:[1,1,0]
	v_pk_fma_f32 v[136:137], v[76:77], v[130:131], v[136:137]
	v_pk_fma_f32 v[136:137], v[84:85], v[132:133], v[136:137]
	v_pk_mul_f32 v[136:137], v[134:135], v[136:137]
	v_cvt_pk_bf16_f32 v142, v136, v137
	v_lshlrev_b32_e32 v128, 16, v11
	v_and_b32_e32 v129, 0xffff0000, v11
	v_lshlrev_b32_e32 v130, 16, v15
	v_and_b32_e32 v131, 0xffff0000, v15
	v_lshlrev_b32_e32 v132, 16, v19
	v_and_b32_e32 v133, 0xffff0000, v19
	v_lshlrev_b32_e32 v134, 16, v123
	v_and_b32_e32 v135, 0xffff0000, v123
	v_pk_fma_f32 v[136:137], v[70:71], v[128:129], 0 op_sel_hi:[1,1,0]
	v_pk_fma_f32 v[136:137], v[78:79], v[130:131], v[136:137]
	v_pk_fma_f32 v[136:137], v[86:87], v[132:133], v[136:137]
	v_pk_mul_f32 v[136:137], v[134:135], v[136:137]
	v_cvt_pk_bf16_f32 v143, v136, v137
	global_store_dwordx4 v[96:97], v[140:143], off
	v_cndmask_b32_e64 v28, 0, v28, s[42:43]
	v_cndmask_b32_e64 v29, 0, v29, s[42:43]
	v_cndmask_b32_e64 v30, 0, v30, s[42:43]
	v_cndmask_b32_e64 v31, 0, v31, s[42:43]
	s_waitcnt lgkmcnt(0)
	v_lshlrev_b32_e32 v128, 16, v20
	v_and_b32_e32 v129, 0xffff0000, v20
	v_lshlrev_b32_e32 v130, 16, v24
	v_and_b32_e32 v131, 0xffff0000, v24
	v_lshlrev_b32_e32 v132, 16, v28
	v_and_b32_e32 v133, 0xffff0000, v28
	v_lshlrev_b32_e32 v134, 16, v124
	v_and_b32_e32 v135, 0xffff0000, v124
	v_pk_fma_f32 v[136:137], v[64:65], v[128:129], 0 op_sel_hi:[1,1,0]
	v_pk_fma_f32 v[136:137], v[72:73], v[130:131], v[136:137]
	v_pk_fma_f32 v[136:137], v[80:81], v[132:133], v[136:137]
	v_pk_mul_f32 v[136:137], v[134:135], v[136:137]
	v_cvt_pk_bf16_f32 v144, v136, v137
	v_lshlrev_b32_e32 v128, 16, v21
	v_and_b32_e32 v129, 0xffff0000, v21
	v_lshlrev_b32_e32 v130, 16, v25
	v_and_b32_e32 v131, 0xffff0000, v25
	v_lshlrev_b32_e32 v132, 16, v29
	v_and_b32_e32 v133, 0xffff0000, v29
	v_lshlrev_b32_e32 v134, 16, v125
	v_and_b32_e32 v135, 0xffff0000, v125
	v_pk_fma_f32 v[136:137], v[66:67], v[128:129], 0 op_sel_hi:[1,1,0]
	v_pk_fma_f32 v[136:137], v[74:75], v[130:131], v[136:137]
	v_pk_fma_f32 v[136:137], v[82:83], v[132:133], v[136:137]
	v_pk_mul_f32 v[136:137], v[134:135], v[136:137]
	v_cvt_pk_bf16_f32 v145, v136, v137
	v_lshlrev_b32_e32 v128, 16, v22
	v_and_b32_e32 v129, 0xffff0000, v22
	v_lshlrev_b32_e32 v130, 16, v26
	v_and_b32_e32 v131, 0xffff0000, v26
	v_lshlrev_b32_e32 v132, 16, v30
	v_and_b32_e32 v133, 0xffff0000, v30
	v_lshlrev_b32_e32 v134, 16, v126
	v_and_b32_e32 v135, 0xffff0000, v126
	v_pk_fma_f32 v[136:137], v[68:69], v[128:129], 0 op_sel_hi:[1,1,0]
	v_pk_fma_f32 v[136:137], v[76:77], v[130:131], v[136:137]
	v_pk_fma_f32 v[136:137], v[84:85], v[132:133], v[136:137]
	v_pk_mul_f32 v[136:137], v[134:135], v[136:137]
	v_cvt_pk_bf16_f32 v146, v136, v137
	v_lshlrev_b32_e32 v128, 16, v23
	v_and_b32_e32 v129, 0xffff0000, v23
	v_lshlrev_b32_e32 v130, 16, v27
	v_and_b32_e32 v131, 0xffff0000, v27
	v_lshlrev_b32_e32 v132, 16, v31
	v_and_b32_e32 v133, 0xffff0000, v31
	v_lshlrev_b32_e32 v134, 16, v127
	v_and_b32_e32 v135, 0xffff0000, v127
	v_pk_fma_f32 v[136:137], v[70:71], v[128:129], 0 op_sel_hi:[1,1,0]
	v_pk_fma_f32 v[136:137], v[78:79], v[130:131], v[136:137]
	v_pk_fma_f32 v[136:137], v[86:87], v[132:133], v[136:137]
	v_pk_mul_f32 v[136:137], v[134:135], v[136:137]
	v_cvt_pk_bf16_f32 v147, v136, v137
	global_store_dwordx4 v[98:99], v[144:147], off
	v_lshl_add_u64 v[96:97], v[96:97], 0, s[48:49]
	v_lshl_add_u64 v[98:99], v[98:99], 0, s[48:49]
	global_load_dwordx4 v[0:3], v[88:89], off
	global_load_dwordx4 v[4:7], v[90:91], off
	global_load_dwordx4 v[8:11], v[92:93], off offset:-3072
	global_load_dwordx4 v[12:15], v[92:93], off offset:0
	global_load_dwordx4 v[16:19], v[92:93], off offset:3072
	global_load_dwordx4 v[20:23], v[94:95], off offset:-3072
	global_load_dwordx4 v[24:27], v[94:95], off offset:0
	global_load_dwordx4 v[28:31], v[94:95], off offset:3072
	v_lshl_add_u64 v[88:89], v[88:89], 0, s[44:45]
	v_lshl_add_u64 v[90:91], v[90:91], 0, s[44:45]
	v_lshl_add_u64 v[92:93], v[92:93], 0, s[46:47]
	v_lshl_add_u64 v[94:95], v[94:95], 0, s[46:47]
	s_waitcnt vmcnt(10)
	ds_write_b16 v117, v32 offset:9216
	ds_write_b16_d16_hi v117, v32 offset:9360
	ds_write_b16 v117, v33 offset:9504
	ds_write_b16_d16_hi v117, v33 offset:9648
	ds_write_b16 v117, v34 offset:9792
	ds_write_b16_d16_hi v117, v34 offset:9936
	ds_write_b16 v117, v35 offset:10080
	ds_write_b16_d16_hi v117, v35 offset:10224
	ds_write_b16 v117, v36 offset:9280
	ds_write_b16_d16_hi v117, v36 offset:9424
	ds_write_b16 v117, v37 offset:9568
	ds_write_b16_d16_hi v117, v37 offset:9712
	ds_write_b16 v117, v38 offset:9856
	ds_write_b16_d16_hi v117, v38 offset:10000
	ds_write_b16 v117, v39 offset:10144
	ds_write_b16_d16_hi v117, v39 offset:10288
	s_waitcnt lgkmcnt(0)
	s_barrier
; DI float bflo(unsigned u) { return __uint_as_float(u << 16); }
; DI float bfhi(unsigned u) { return __uint_as_float(u & 0xffff0000u); }
; DI void hyena_post_tile(const Params& p, int item, char* smem) {
;     ...
; #pragma unroll
;   for (int i = 0; i < 2; ++i) {
;     int row = (tid >> 3) + 32 * i, ck = tid & 7;
;     u32x4 u = ldg16(yT + ((size_t)(ct * 64 + row) * 8 + b) * 4096 + st * 64 + ck * 8);
; #pragma unroll
;     for (int j = 0; j < 8; ++j) { unsigned wv = u[j >> 1]; sT[(ck * 8 + j) * 72 + row] = (bf16_t)((j & 1) ? (wv >> 16) : (wv & 0xffffu)); }
;   }
;     ...
;   bf16_t* CD = (bf16_t*)(p.ws + OFF_AB);
; #pragma unroll
;   for (int i = 0; i < 2; ++i) {
;     int row = (tid >> 3) + 32 * i, ck = tid & 7, s = st * 64 + row, c = ct * 64 + ck * 8;
;     float x0[8];
; #pragma unroll
;     for (int j = 0; j < 8; ++j) x0[j] = 0.f;
; #pragma unroll
;     for (int d = -1; d <= 1; ++d) {
;       int ss = s + d;
;       if (ss >= 0 && ss < 4096) {
;         u32x4 a = ldg16(HY + (size_t)ss * 1536 + c);
;         float wa[8]; ld8f(p.c_short + (d + 1) * 1536 + c, wa);
; #pragma unroll
;         for (int q = 0; q < 4; ++q) { x0[2 * q] += wa[2 * q] * bflo(a[q]); x0[2 * q + 1] += wa[2 * q + 1] * bfhi(a[q]); }
;       }
;     }
;     u32x4 y = *(const u32x4*)(sT + row * 72 + ck * 8);
;     float v[8];
; #pragma unroll
;     for (int q = 0; q < 4; ++q) { v[2 * q] = bflo(y[q]) * x0[2 * q]; v[2 * q + 1] = bfhi(y[q]) * x0[2 * q + 1]; }
;     store8(CD + ((size_t)b * 4096 + s) * 1024 + 512 + c, v);
;   }
	ds_read_b128 v[120:123], v118 offset:9216
	ds_read_b128 v[124:127], v118 offset:13824
	v_cndmask_b32_e64 v40, 0, v40, s[40:41]
	v_cndmask_b32_e64 v41, 0, v41, s[40:41]
	v_cndmask_b32_e64 v42, 0, v42, s[40:41]
	v_cndmask_b32_e64 v43, 0, v43, s[40:41]
	s_waitcnt lgkmcnt(1)
	v_lshlrev_b32_e32 v128, 16, v40
	v_and_b32_e32 v129, 0xffff0000, v40
	v_lshlrev_b32_e32 v130, 16, v44
	v_and_b32_e32 v131, 0xffff0000, v44
	v_lshlrev_b32_e32 v132, 16, v48
	v_and_b32_e32 v133, 0xffff0000, v48
	v_lshlrev_b32_e32 v134, 16, v120
	v_and_b32_e32 v135, 0xffff0000, v120
	v_pk_fma_f32 v[136:137], v[64:65], v[128:129], 0 op_sel_hi:[1,1,0]
	v_pk_fma_f32 v[136:137], v[72:73], v[130:131], v[136:137]
	v_pk_fma_f32 v[136:137], v[80:81], v[132:133], v[136:137]
	v_pk_mul_f32 v[136:137], v[134:135], v[136:137]
	v_cvt_pk_bf16_f32 v140, v136, v137
	v_lshlrev_b32_e32 v128, 16, v41
	v_and_b32_e32 v129, 0xffff0000, v41
	v_lshlrev_b32_e32 v130, 16, v45
	v_and_b32_e32 v131, 0xffff0000, v45
	v_lshlrev_b32_e32 v132, 16, v49
	v_and_b32_e32 v133, 0xffff0000, v49
	v_lshlrev_b32_e32 v134, 16, v121
	v_and_b32_e32 v135, 0xffff0000, v121
	v_pk_fma_f32 v[136:137], v[66:67], v[128:129], 0 op_sel_hi:[1,1,0]
	v_pk_fma_f32 v[136:137], v[74:75], v[130:131], v[136:137]
	v_pk_fma_f32 v[136:137], v[82:83], v[132:133], v[136:137]
	v_pk_mul_f32 v[136:137], v[134:135], v[136:137]
	v_cvt_pk_bf16_f32 v141, v136, v137
	v_lshlrev_b32_e32 v128, 16, v42
	v_and_b32_e32 v129, 0xffff0000, v42
	v_lshlrev_b32_e32 v130, 16, v46
	v_and_b32_e32 v131, 0xffff0000, v46
	v_lshlrev_b32_e32 v132, 16, v50
	v_and_b32_e32 v133, 0xffff0000, v50
	v_lshlrev_b32_e32 v134, 16, v122
	v_and_b32_e32 v135, 0xffff0000, v122
	v_pk_fma_f32 v[136:137], v[68:69], v[128:129], 0 op_sel_hi:[1,1,0]
	v_pk_fma_f32 v[136:137], v[76:77], v[130:131], v[136:137]
	v_pk_fma_f32 v[136:137], v[84:85], v[132:133], v[136:137]
	v_pk_mul_f32 v[136:137], v[134:135], v[136:137]
	v_cvt_pk_bf16_f32 v142, v136, v137
	v_lshlrev_b32_e32 v128, 16, v43
	v_and_b32_e32 v129, 0xffff0000, v43
	v_lshlrev_b32_e32 v130, 16, v47
	v_and_b32_e32 v131, 0xffff0000, v47
	v_lshlrev_b32_e32 v132, 16, v51
	v_and_b32_e32 v133, 0xffff0000, v51
	v_lshlrev_b32_e32 v134, 16, v123
	v_and_b32_e32 v135, 0xffff0000, v123
	v_pk_fma_f32 v[136:137], v[70:71], v[128:129], 0 op_sel_hi:[1,1,0]
	v_pk_fma_f32 v[136:137], v[78:79], v[130:131], v[136:137]
	v_pk_fma_f32 v[136:137], v[86:87], v[132:133], v[136:137]
	v_pk_mul_f32 v[136:137], v[134:135], v[136:137]
	v_cvt_pk_bf16_f32 v143, v136, v137
	global_store_dwordx4 v[96:97], v[140:143], off
	v_cndmask_b32_e64 v60, 0, v60, s[42:43]
	v_cndmask_b32_e64 v61, 0, v61, s[42:43]
	v_cndmask_b32_e64 v62, 0, v62, s[42:43]
	v_cndmask_b32_e64 v63, 0, v63, s[42:43]
	s_waitcnt lgkmcnt(0)
	v_lshlrev_b32_e32 v128, 16, v52
	v_and_b32_e32 v129, 0xffff0000, v52
	v_lshlrev_b32_e32 v130, 16, v56
	v_and_b32_e32 v131, 0xffff0000, v56
	v_lshlrev_b32_e32 v132, 16, v60
	v_and_b32_e32 v133, 0xffff0000, v60
	v_lshlrev_b32_e32 v134, 16, v124
	v_and_b32_e32 v135, 0xffff0000, v124
	v_pk_fma_f32 v[136:137], v[64:65], v[128:129], 0 op_sel_hi:[1,1,0]
	v_pk_fma_f32 v[136:137], v[72:73], v[130:131], v[136:137]
	v_pk_fma_f32 v[136:137], v[80:81], v[132:133], v[136:137]
	v_pk_mul_f32 v[136:137], v[134:135], v[136:137]
	v_cvt_pk_bf16_f32 v144, v136, v137
	v_lshlrev_b32_e32 v128, 16, v53
	v_and_b32_e32 v129, 0xffff0000, v53
	v_lshlrev_b32_e32 v130, 16, v57
	v_and_b32_e32 v131, 0xffff0000, v57
	v_lshlrev_b32_e32 v132, 16, v61
	v_and_b32_e32 v133, 0xffff0000, v61
	v_lshlrev_b32_e32 v134, 16, v125
	v_and_b32_e32 v135, 0xffff0000, v125
	v_pk_fma_f32 v[136:137], v[66:67], v[128:129], 0 op_sel_hi:[1,1,0]
	v_pk_fma_f32 v[136:137], v[74:75], v[130:131], v[136:137]
	v_pk_fma_f32 v[136:137], v[82:83], v[132:133], v[136:137]
	v_pk_mul_f32 v[136:137], v[134:135], v[136:137]
	v_cvt_pk_bf16_f32 v145, v136, v137
	v_lshlrev_b32_e32 v128, 16, v54
	v_and_b32_e32 v129, 0xffff0000, v54
	v_lshlrev_b32_e32 v130, 16, v58
	v_and_b32_e32 v131, 0xffff0000, v58
	v_lshlrev_b32_e32 v132, 16, v62
	v_and_b32_e32 v133, 0xffff0000, v62
	v_lshlrev_b32_e32 v134, 16, v126
	v_and_b32_e32 v135, 0xffff0000, v126
	v_pk_fma_f32 v[136:137], v[68:69], v[128:129], 0 op_sel_hi:[1,1,0]
	v_pk_fma_f32 v[136:137], v[76:77], v[130:131], v[136:137]
	v_pk_fma_f32 v[136:137], v[84:85], v[132:133], v[136:137]
	v_pk_mul_f32 v[136:137], v[134:135], v[136:137]
	v_cvt_pk_bf16_f32 v146, v136, v137
	v_lshlrev_b32_e32 v128, 16, v55
	v_and_b32_e32 v129, 0xffff0000, v55
	v_lshlrev_b32_e32 v130, 16, v59
	v_and_b32_e32 v131, 0xffff0000, v59
	v_lshlrev_b32_e32 v132, 16, v63
	v_and_b32_e32 v133, 0xffff0000, v63
	v_lshlrev_b32_e32 v134, 16, v127
	v_and_b32_e32 v135, 0xffff0000, v127
	v_pk_fma_f32 v[136:137], v[70:71], v[128:129], 0 op_sel_hi:[1,1,0]
	v_pk_fma_f32 v[136:137], v[78:79], v[130:131], v[136:137]
	v_pk_fma_f32 v[136:137], v[86:87], v[132:133], v[136:137]
	v_pk_mul_f32 v[136:137], v[134:135], v[136:137]
	v_cvt_pk_bf16_f32 v147, v136, v137
	global_store_dwordx4 v[98:99], v[144:147], off
	v_lshl_add_u64 v[96:97], v[96:97], 0, s[48:49]
	v_lshl_add_u64 v[98:99], v[98:99], 0, s[48:49]
	global_load_dwordx4 v[32:35], v[88:89], off
	global_load_dwordx4 v[36:39], v[90:91], off
	global_load_dwordx4 v[40:43], v[92:93], off offset:-3072
	global_load_dwordx4 v[44:47], v[92:93], off offset:0
	global_load_dwordx4 v[48:51], v[92:93], off offset:3072
	global_load_dwordx4 v[52:55], v[94:95], off offset:-3072
	global_load_dwordx4 v[56:59], v[94:95], off offset:0
	global_load_dwordx4 v[60:63], v[94:95], off offset:3072
	v_lshl_add_u64 v[88:89], v[88:89], 0, s[44:45]
	v_lshl_add_u64 v[90:91], v[90:91], 0, s[44:45]
	v_lshl_add_u64 v[92:93], v[92:93], 0, s[46:47]
	v_lshl_add_u64 v[94:95], v[94:95], 0, s[46:47]
	s_waitcnt vmcnt(10)
	ds_write_b16 v117, v0
	ds_write_b16_d16_hi v117, v0 offset:144
	ds_write_b16 v117, v1 offset:288
	ds_write_b16_d16_hi v117, v1 offset:432
	ds_write_b16 v117, v2 offset:576
	ds_write_b16_d16_hi v117, v2 offset:720
	ds_write_b16 v117, v3 offset:864
	ds_write_b16_d16_hi v117, v3 offset:1008
	ds_write_b16 v117, v4 offset:64
	ds_write_b16_d16_hi v117, v4 offset:208
	ds_write_b16 v117, v5 offset:352
	ds_write_b16_d16_hi v117, v5 offset:496
	ds_write_b16 v117, v6 offset:640
	ds_write_b16_d16_hi v117, v6 offset:784
	ds_write_b16 v117, v7 offset:928
	ds_write_b16_d16_hi v117, v7 offset:1072
	s_waitcnt lgkmcnt(0)
	s_barrier
; DI float bflo(unsigned u) { return __uint_as_float(u << 16); }
; DI float bfhi(unsigned u) { return __uint_as_float(u & 0xffff0000u); }
; DI void hyena_post_tile(const Params& p, int item, char* smem) {
;     ...
; #pragma unroll
;   for (int i = 0; i < 2; ++i) {
;     int row = (tid >> 3) + 32 * i, ck = tid & 7;
;     u32x4 u = ldg16(yT + ((size_t)(ct * 64 + row) * 8 + b) * 4096 + st * 64 + ck * 8);
; #pragma unroll
;     for (int j = 0; j < 8; ++j) { unsigned wv = u[j >> 1]; sT[(ck * 8 + j) * 72 + row] = (bf16_t)((j & 1) ? (wv >> 16) : (wv & 0xffffu)); }
;   }
;     ...
;   bf16_t* CD = (bf16_t*)(p.ws + OFF_AB);
; #pragma unroll
;   for (int i = 0; i < 2; ++i) {
;     int row = (tid >> 3) + 32 * i, ck = tid & 7, s = st * 64 + row, c = ct * 64 + ck * 8;
;     float x0[8];
; #pragma unroll
;     for (int j = 0; j < 8; ++j) x0[j] = 0.f;
; #pragma unroll
;     for (int d = -1; d <= 1; ++d) {
;       int ss = s + d;
;       if (ss >= 0 && ss < 4096) {
;         u32x4 a = ldg16(HY + (size_t)ss * 1536 + c);
;         float wa[8]; ld8f(p.c_short + (d + 1) * 1536 + c, wa);
; #pragma unroll
;         for (int q = 0; q < 4; ++q) { x0[2 * q] += wa[2 * q] * bflo(a[q]); x0[2 * q + 1] += wa[2 * q + 1] * bfhi(a[q]); }
;       }
;     }
;     u32x4 y = *(const u32x4*)(sT + row * 72 + ck * 8);
;     float v[8];
; #pragma unroll
;     for (int q = 0; q < 4; ++q) { v[2 * q] = bflo(y[q]) * x0[2 * q]; v[2 * q + 1] = bfhi(y[q]) * x0[2 * q + 1]; }
;     store8(CD + ((size_t)b * 4096 + s) * 1024 + 512 + c, v);
;   }
	ds_read_b128 v[120:123], v118
	ds_read_b128 v[124:127], v118 offset:4608
	v_cndmask_b32_e64 v8, 0, v8, s[40:41]
	v_cndmask_b32_e64 v9, 0, v9, s[40:41]
	v_cndmask_b32_e64 v10, 0, v10, s[40:41]
	v_cndmask_b32_e64 v11, 0, v11, s[40:41]
	s_waitcnt lgkmcnt(1)
	v_lshlrev_b32_e32 v128, 16, v8
	v_and_b32_e32 v129, 0xffff0000, v8
	v_lshlrev_b32_e32 v130, 16, v12
	v_and_b32_e32 v131, 0xffff0000, v12
	v_lshlrev_b32_e32 v132, 16, v16
	v_and_b32_e32 v133, 0xffff0000, v16
	v_lshlrev_b32_e32 v134, 16, v120
	v_and_b32_e32 v135, 0xffff0000, v120
	v_pk_fma_f32 v[136:137], v[64:65], v[128:129], 0 op_sel_hi:[1,1,0]
	v_pk_fma_f32 v[136:137], v[72:73], v[130:131], v[136:137]
	v_pk_fma_f32 v[136:137], v[80:81], v[132:133], v[136:137]
	v_pk_mul_f32 v[136:137], v[134:135], v[136:137]
	v_cvt_pk_bf16_f32 v140, v136, v137
	v_lshlrev_b32_e32 v128, 16, v9
	v_and_b32_e32 v129, 0xffff0000, v9
	v_lshlrev_b32_e32 v130, 16, v13
	v_and_b32_e32 v131, 0xffff0000, v13
	v_lshlrev_b32_e32 v132, 16, v17
	v_and_b32_e32 v133, 0xffff0000, v17
	v_lshlrev_b32_e32 v134, 16, v121
	v_and_b32_e32 v135, 0xffff0000, v121
	v_pk_fma_f32 v[136:137], v[66:67], v[128:129], 0 op_sel_hi:[1,1,0]
	v_pk_fma_f32 v[136:137], v[74:75], v[130:131], v[136:137]
	v_pk_fma_f32 v[136:137], v[82:83], v[132:133], v[136:137]
	v_pk_mul_f32 v[136:137], v[134:135], v[136:137]
	v_cvt_pk_bf16_f32 v141, v136, v137
	v_lshlrev_b32_e32 v128, 16, v10
	v_and_b32_e32 v129, 0xffff0000, v10
	v_lshlrev_b32_e32 v130, 16, v14
	v_and_b32_e32 v131, 0xffff0000, v14
	v_lshlrev_b32_e32 v132, 16, v18
	v_and_b32_e32 v133, 0xffff0000, v18
	v_lshlrev_b32_e32 v134, 16, v122
	v_and_b32_e32 v135, 0xffff0000, v122
	v_pk_fma_f32 v[136:137], v[68:69], v[128:129], 0 op_sel_hi:[1,1,0]
	v_pk_fma_f32 v[136:137], v[76:77], v[130:131], v[136:137]
	v_pk_fma_f32 v[136:137], v[84:85], v[132:133], v[136:137]
	v_pk_mul_f32 v[136:137], v[134:135], v[136:137]
	v_cvt_pk_bf16_f32 v142, v136, v137
	v_lshlrev_b32_e32 v128, 16, v11
	v_and_b32_e32 v129, 0xffff0000, v11
	v_lshlrev_b32_e32 v130, 16, v15
	v_and_b32_e32 v131, 0xffff0000, v15
	v_lshlrev_b32_e32 v132, 16, v19
	v_and_b32_e32 v133, 0xffff0000, v19
	v_lshlrev_b32_e32 v134, 16, v123
	v_and_b32_e32 v135, 0xffff0000, v123
	v_pk_fma_f32 v[136:137], v[70:71], v[128:129], 0 op_sel_hi:[1,1,0]
	v_pk_fma_f32 v[136:137], v[78:79], v[130:131], v[136:137]
	v_pk_fma_f32 v[136:137], v[86:87], v[132:133], v[136:137]
	v_pk_mul_f32 v[136:137], v[134:135], v[136:137]
	v_cvt_pk_bf16_f32 v143, v136, v137
	global_store_dwordx4 v[96:97], v[140:143], off
	v_cndmask_b32_e64 v28, 0, v28, s[42:43]
	v_cndmask_b32_e64 v29, 0, v29, s[42:43]
	v_cndmask_b32_e64 v30, 0, v30, s[42:43]
	v_cndmask_b32_e64 v31, 0, v31, s[42:43]
	s_waitcnt lgkmcnt(0)
	v_lshlrev_b32_e32 v128, 16, v20
	v_and_b32_e32 v129, 0xffff0000, v20
	v_lshlrev_b32_e32 v130, 16, v24
	v_and_b32_e32 v131, 0xffff0000, v24
	v_lshlrev_b32_e32 v132, 16, v28
	v_and_b32_e32 v133, 0xffff0000, v28
	v_lshlrev_b32_e32 v134, 16, v124
	v_and_b32_e32 v135, 0xffff0000, v124
	v_pk_fma_f32 v[136:137], v[64:65], v[128:129], 0 op_sel_hi:[1,1,0]
	v_pk_fma_f32 v[136:137], v[72:73], v[130:131], v[136:137]
	v_pk_fma_f32 v[136:137], v[80:81], v[132:133], v[136:137]
	v_pk_mul_f32 v[136:137], v[134:135], v[136:137]
	v_cvt_pk_bf16_f32 v144, v136, v137
	v_lshlrev_b32_e32 v128, 16, v21
	v_and_b32_e32 v129, 0xffff0000, v21
	v_lshlrev_b32_e32 v130, 16, v25
	v_and_b32_e32 v131, 0xffff0000, v25
	v_lshlrev_b32_e32 v132, 16, v29
	v_and_b32_e32 v133, 0xffff0000, v29
	v_lshlrev_b32_e32 v134, 16, v125
	v_and_b32_e32 v135, 0xffff0000, v125
	v_pk_fma_f32 v[136:137], v[66:67], v[128:129], 0 op_sel_hi:[1,1,0]
	v_pk_fma_f32 v[136:137], v[74:75], v[130:131], v[136:137]
	v_pk_fma_f32 v[136:137], v[82:83], v[132:133], v[136:137]
	v_pk_mul_f32 v[136:137], v[134:135], v[136:137]
	v_cvt_pk_bf16_f32 v145, v136, v137
	v_lshlrev_b32_e32 v128, 16, v22
	v_and_b32_e32 v129, 0xffff0000, v22
	v_lshlrev_b32_e32 v130, 16, v26
	v_and_b32_e32 v131, 0xffff0000, v26
	v_lshlrev_b32_e32 v132, 16, v30
	v_and_b32_e32 v133, 0xffff0000, v30
	v_lshlrev_b32_e32 v134, 16, v126
	v_and_b32_e32 v135, 0xffff0000, v126
	v_pk_fma_f32 v[136:137], v[68:69], v[128:129], 0 op_sel_hi:[1,1,0]
	v_pk_fma_f32 v[136:137], v[76:77], v[130:131], v[136:137]
	v_pk_fma_f32 v[136:137], v[84:85], v[132:133], v[136:137]
	v_pk_mul_f32 v[136:137], v[134:135], v[136:137]
	v_cvt_pk_bf16_f32 v146, v136, v137
	v_lshlrev_b32_e32 v128, 16, v23
	v_and_b32_e32 v129, 0xffff0000, v23
	v_lshlrev_b32_e32 v130, 16, v27
	v_and_b32_e32 v131, 0xffff0000, v27
	v_lshlrev_b32_e32 v132, 16, v31
	v_and_b32_e32 v133, 0xffff0000, v31
	v_lshlrev_b32_e32 v134, 16, v127
	v_and_b32_e32 v135, 0xffff0000, v127
	v_pk_fma_f32 v[136:137], v[70:71], v[128:129], 0 op_sel_hi:[1,1,0]
	v_pk_fma_f32 v[136:137], v[78:79], v[130:131], v[136:137]
	v_pk_fma_f32 v[136:137], v[86:87], v[132:133], v[136:137]
	v_pk_mul_f32 v[136:137], v[134:135], v[136:137]
	v_cvt_pk_bf16_f32 v147, v136, v137
	global_store_dwordx4 v[98:99], v[144:147], off
	v_lshl_add_u64 v[96:97], v[96:97], 0, s[48:49]
	v_lshl_add_u64 v[98:99], v[98:99], 0, s[48:49]
	global_load_dwordx4 v[0:3], v[88:89], off
	global_load_dwordx4 v[4:7], v[90:91], off
	global_load_dwordx4 v[8:11], v[92:93], off offset:-3072
	global_load_dwordx4 v[12:15], v[92:93], off offset:0
	global_load_dwordx4 v[16:19], v[92:93], off offset:3072
	global_load_dwordx4 v[20:23], v[94:95], off offset:-3072
	global_load_dwordx4 v[24:27], v[94:95], off offset:0
	global_load_dwordx4 v[28:31], v[94:95], off offset:3072
	v_lshl_add_u64 v[88:89], v[88:89], 0, s[44:45]
	v_lshl_add_u64 v[90:91], v[90:91], 0, s[44:45]
	v_lshl_add_u64 v[92:93], v[92:93], 0, s[46:47]
	v_lshl_add_u64 v[94:95], v[94:95], 0, s[46:47]
	s_waitcnt vmcnt(10)
	ds_write_b16 v117, v32 offset:9216
	ds_write_b16_d16_hi v117, v32 offset:9360
	ds_write_b16 v117, v33 offset:9504
	ds_write_b16_d16_hi v117, v33 offset:9648
	ds_write_b16 v117, v34 offset:9792
	ds_write_b16_d16_hi v117, v34 offset:9936
	ds_write_b16 v117, v35 offset:10080
	ds_write_b16_d16_hi v117, v35 offset:10224
	ds_write_b16 v117, v36 offset:9280
	ds_write_b16_d16_hi v117, v36 offset:9424
	ds_write_b16 v117, v37 offset:9568
	ds_write_b16_d16_hi v117, v37 offset:9712
	ds_write_b16 v117, v38 offset:9856
	ds_write_b16_d16_hi v117, v38 offset:10000
	ds_write_b16 v117, v39 offset:10144
	ds_write_b16_d16_hi v117, v39 offset:10288
	s_waitcnt lgkmcnt(0)
	s_barrier
; DI float bflo(unsigned u) { return __uint_as_float(u << 16); }
; DI float bfhi(unsigned u) { return __uint_as_float(u & 0xffff0000u); }
; DI void hyena_post_tile(const Params& p, int item, char* smem) {
;     ...
; #pragma unroll
;   for (int i = 0; i < 2; ++i) {
;     int row = (tid >> 3) + 32 * i, ck = tid & 7;
;     u32x4 u = ldg16(yT + ((size_t)(ct * 64 + row) * 8 + b) * 4096 + st * 64 + ck * 8);
; #pragma unroll
;     for (int j = 0; j < 8; ++j) { unsigned wv = u[j >> 1]; sT[(ck * 8 + j) * 72 + row] = (bf16_t)((j & 1) ? (wv >> 16) : (wv & 0xffffu)); }
;   }
;     ...
;   bf16_t* CD = (bf16_t*)(p.ws + OFF_AB);
; #pragma unroll
;   for (int i = 0; i < 2; ++i) {
;     int row = (tid >> 3) + 32 * i, ck = tid & 7, s = st * 64 + row, c = ct * 64 + ck * 8;
;     float x0[8];
; #pragma unroll
;     for (int j = 0; j < 8; ++j) x0[j] = 0.f;
; #pragma unroll
;     for (int d = -1; d <= 1; ++d) {
;       int ss = s + d;
;       if (ss >= 0 && ss < 4096) {
;         u32x4 a = ldg16(HY + (size_t)ss * 1536 + c);
;         float wa[8]; ld8f(p.c_short + (d + 1) * 1536 + c, wa);
; #pragma unroll
;         for (int q = 0; q < 4; ++q) { x0[2 * q] += wa[2 * q] * bflo(a[q]); x0[2 * q + 1] += wa[2 * q + 1] * bfhi(a[q]); }
;       }
;     }
;     u32x4 y = *(const u32x4*)(sT + row * 72 + ck * 8);
;     float v[8];
; #pragma unroll
;     for (int q = 0; q < 4; ++q) { v[2 * q] = bflo(y[q]) * x0[2 * q]; v[2 * q + 1] = bfhi(y[q]) * x0[2 * q + 1]; }
;     store8(CD + ((size_t)b * 4096 + s) * 1024 + 512 + c, v);
;   }
	ds_read_b128 v[120:123], v118 offset:9216
	ds_read_b128 v[124:127], v118 offset:13824
	v_cndmask_b32_e64 v40, 0, v40, s[40:41]
	v_cndmask_b32_e64 v41, 0, v41, s[40:41]
	v_cndmask_b32_e64 v42, 0, v42, s[40:41]
	v_cndmask_b32_e64 v43, 0, v43, s[40:41]
	s_waitcnt lgkmcnt(1)
	v_lshlrev_b32_e32 v128, 16, v40
	v_and_b32_e32 v129, 0xffff0000, v40
	v_lshlrev_b32_e32 v130, 16, v44
	v_and_b32_e32 v131, 0xffff0000, v44
	v_lshlrev_b32_e32 v132, 16, v48
	v_and_b32_e32 v133, 0xffff0000, v48
	v_lshlrev_b32_e32 v134, 16, v120
	v_and_b32_e32 v135, 0xffff0000, v120
	v_pk_fma_f32 v[136:137], v[64:65], v[128:129], 0 op_sel_hi:[1,1,0]
	v_pk_fma_f32 v[136:137], v[72:73], v[130:131], v[136:137]
	v_pk_fma_f32 v[136:137], v[80:81], v[132:133], v[136:137]
	v_pk_mul_f32 v[136:137], v[134:135], v[136:137]
	v_cvt_pk_bf16_f32 v140, v136, v137
	v_lshlrev_b32_e32 v128, 16, v41
	v_and_b32_e32 v129, 0xffff0000, v41
	v_lshlrev_b32_e32 v130, 16, v45
	v_and_b32_e32 v131, 0xffff0000, v45
	v_lshlrev_b32_e32 v132, 16, v49
	v_and_b32_e32 v133, 0xffff0000, v49
	v_lshlrev_b32_e32 v134, 16, v121
	v_and_b32_e32 v135, 0xffff0000, v121
	v_pk_fma_f32 v[136:137], v[66:67], v[128:129], 0 op_sel_hi:[1,1,0]
	v_pk_fma_f32 v[136:137], v[74:75], v[130:131], v[136:137]
	v_pk_fma_f32 v[136:137], v[82:83], v[132:133], v[136:137]
	v_pk_mul_f32 v[136:137], v[134:135], v[136:137]
	v_cvt_pk_bf16_f32 v141, v136, v137
	v_lshlrev_b32_e32 v128, 16, v42
	v_and_b32_e32 v129, 0xffff0000, v42
	v_lshlrev_b32_e32 v130, 16, v46
	v_and_b32_e32 v131, 0xffff0000, v46
	v_lshlrev_b32_e32 v132, 16, v50
	v_and_b32_e32 v133, 0xffff0000, v50
	v_lshlrev_b32_e32 v134, 16, v122
	v_and_b32_e32 v135, 0xffff0000, v122
	v_pk_fma_f32 v[136:137], v[68:69], v[128:129], 0 op_sel_hi:[1,1,0]
	v_pk_fma_f32 v[136:137], v[76:77], v[130:131], v[136:137]
	v_pk_fma_f32 v[136:137], v[84:85], v[132:133], v[136:137]
	v_pk_mul_f32 v[136:137], v[134:135], v[136:137]
	v_cvt_pk_bf16_f32 v142, v136, v137
	v_lshlrev_b32_e32 v128, 16, v43
	v_and_b32_e32 v129, 0xffff0000, v43
	v_lshlrev_b32_e32 v130, 16, v47
	v_and_b32_e32 v131, 0xffff0000, v47
	v_lshlrev_b32_e32 v132, 16, v51
	v_and_b32_e32 v133, 0xffff0000, v51
	v_lshlrev_b32_e32 v134, 16, v123
	v_and_b32_e32 v135, 0xffff0000, v123
	v_pk_fma_f32 v[136:137], v[70:71], v[128:129], 0 op_sel_hi:[1,1,0]
	v_pk_fma_f32 v[136:137], v[78:79], v[130:131], v[136:137]
	v_pk_fma_f32 v[136:137], v[86:87], v[132:133], v[136:137]
	v_pk_mul_f32 v[136:137], v[134:135], v[136:137]
	v_cvt_pk_bf16_f32 v143, v136, v137
	global_store_dwordx4 v[96:97], v[140:143], off
	v_cndmask_b32_e64 v60, 0, v60, s[42:43]
	v_cndmask_b32_e64 v61, 0, v61, s[42:43]
	v_cndmask_b32_e64 v62, 0, v62, s[42:43]
	v_cndmask_b32_e64 v63, 0, v63, s[42:43]
	s_waitcnt lgkmcnt(0)
	v_lshlrev_b32_e32 v128, 16, v52
	v_and_b32_e32 v129, 0xffff0000, v52
	v_lshlrev_b32_e32 v130, 16, v56
	v_and_b32_e32 v131, 0xffff0000, v56
	v_lshlrev_b32_e32 v132, 16, v60
	v_and_b32_e32 v133, 0xffff0000, v60
	v_lshlrev_b32_e32 v134, 16, v124
	v_and_b32_e32 v135, 0xffff0000, v124
	v_pk_fma_f32 v[136:137], v[64:65], v[128:129], 0 op_sel_hi:[1,1,0]
	v_pk_fma_f32 v[136:137], v[72:73], v[130:131], v[136:137]
	v_pk_fma_f32 v[136:137], v[80:81], v[132:133], v[136:137]
	v_pk_mul_f32 v[136:137], v[134:135], v[136:137]
	v_cvt_pk_bf16_f32 v144, v136, v137
	v_lshlrev_b32_e32 v128, 16, v53
	v_and_b32_e32 v129, 0xffff0000, v53
	v_lshlrev_b32_e32 v130, 16, v57
	v_and_b32_e32 v131, 0xffff0000, v57
	v_lshlrev_b32_e32 v132, 16, v61
	v_and_b32_e32 v133, 0xffff0000, v61
	v_lshlrev_b32_e32 v134, 16, v125
	v_and_b32_e32 v135, 0xffff0000, v125
	v_pk_fma_f32 v[136:137], v[66:67], v[128:129], 0 op_sel_hi:[1,1,0]
	v_pk_fma_f32 v[136:137], v[74:75], v[130:131], v[136:137]
	v_pk_fma_f32 v[136:137], v[82:83], v[132:133], v[136:137]
	v_pk_mul_f32 v[136:137], v[134:135], v[136:137]
	v_cvt_pk_bf16_f32 v145, v136, v137
	v_lshlrev_b32_e32 v128, 16, v54
	v_and_b32_e32 v129, 0xffff0000, v54
	v_lshlrev_b32_e32 v130, 16, v58
	v_and_b32_e32 v131, 0xffff0000, v58
	v_lshlrev_b32_e32 v132, 16, v62
	v_and_b32_e32 v133, 0xffff0000, v62
	v_lshlrev_b32_e32 v134, 16, v126
	v_and_b32_e32 v135, 0xffff0000, v126
	v_pk_fma_f32 v[136:137], v[68:69], v[128:129], 0 op_sel_hi:[1,1,0]
	v_pk_fma_f32 v[136:137], v[76:77], v[130:131], v[136:137]
	v_pk_fma_f32 v[136:137], v[84:85], v[132:133], v[136:137]
	v_pk_mul_f32 v[136:137], v[134:135], v[136:137]
	v_cvt_pk_bf16_f32 v146, v136, v137
	v_lshlrev_b32_e32 v128, 16, v55
	v_and_b32_e32 v129, 0xffff0000, v55
	v_lshlrev_b32_e32 v130, 16, v59
	v_and_b32_e32 v131, 0xffff0000, v59
	v_lshlrev_b32_e32 v132, 16, v63
	v_and_b32_e32 v133, 0xffff0000, v63
	v_lshlrev_b32_e32 v134, 16, v127
	v_and_b32_e32 v135, 0xffff0000, v127
	v_pk_fma_f32 v[136:137], v[70:71], v[128:129], 0 op_sel_hi:[1,1,0]
	v_pk_fma_f32 v[136:137], v[78:79], v[130:131], v[136:137]
	v_pk_fma_f32 v[136:137], v[86:87], v[132:133], v[136:137]
	v_pk_mul_f32 v[136:137], v[134:135], v[136:137]
	v_cvt_pk_bf16_f32 v147, v136, v137
	global_store_dwordx4 v[98:99], v[144:147], off
	v_lshl_add_u64 v[96:97], v[96:97], 0, s[48:49]
	v_lshl_add_u64 v[98:99], v[98:99], 0, s[48:49]
	global_load_dwordx4 v[32:35], v[88:89], off
	global_load_dwordx4 v[36:39], v[90:91], off
	global_load_dwordx4 v[40:43], v[92:93], off offset:-3072
	global_load_dwordx4 v[44:47], v[92:93], off offset:0
	global_load_dwordx4 v[48:51], v[92:93], off offset:3072
	global_load_dwordx4 v[52:55], v[94:95], off offset:-3072
	global_load_dwordx4 v[56:59], v[94:95], off offset:0
	global_load_dwordx4 v[60:63], v[94:95], off offset:3072
	v_lshl_add_u64 v[88:89], v[88:89], 0, s[44:45]
	v_lshl_add_u64 v[90:91], v[90:91], 0, s[44:45]
	v_lshl_add_u64 v[92:93], v[92:93], 0, s[46:47]
	v_lshl_add_u64 v[94:95], v[94:95], 0, s[46:47]
	s_waitcnt vmcnt(10)
	ds_write_b16 v117, v0
	ds_write_b16_d16_hi v117, v0 offset:144
	ds_write_b16 v117, v1 offset:288
	ds_write_b16_d16_hi v117, v1 offset:432
	ds_write_b16 v117, v2 offset:576
	ds_write_b16_d16_hi v117, v2 offset:720
	ds_write_b16 v117, v3 offset:864
	ds_write_b16_d16_hi v117, v3 offset:1008
	ds_write_b16 v117, v4 offset:64
	ds_write_b16_d16_hi v117, v4 offset:208
	ds_write_b16 v117, v5 offset:352
	ds_write_b16_d16_hi v117, v5 offset:496
	ds_write_b16 v117, v6 offset:640
	ds_write_b16_d16_hi v117, v6 offset:784
	ds_write_b16 v117, v7 offset:928
	ds_write_b16_d16_hi v117, v7 offset:1072
	s_waitcnt lgkmcnt(0)
	s_barrier
; DI float bflo(unsigned u) { return __uint_as_float(u << 16); }
; DI float bfhi(unsigned u) { return __uint_as_float(u & 0xffff0000u); }
; DI void hyena_post_tile(const Params& p, int item, char* smem) {
;     ...
; #pragma unroll
;   for (int i = 0; i < 2; ++i) {
;     int row = (tid >> 3) + 32 * i, ck = tid & 7;
;     u32x4 u = ldg16(yT + ((size_t)(ct * 64 + row) * 8 + b) * 4096 + st * 64 + ck * 8);
; #pragma unroll
;     for (int j = 0; j < 8; ++j) { unsigned wv = u[j >> 1]; sT[(ck * 8 + j) * 72 + row] = (bf16_t)((j & 1) ? (wv >> 16) : (wv & 0xffffu)); }
;   }
;     ...
;   bf16_t* CD = (bf16_t*)(p.ws + OFF_AB);
; #pragma unroll
;   for (int i = 0; i < 2; ++i) {
;     int row = (tid >> 3) + 32 * i, ck = tid & 7, s = st * 64 + row, c = ct * 64 + ck * 8;
;     float x0[8];
; #pragma unroll
;     for (int j = 0; j < 8; ++j) x0[j] = 0.f;
; #pragma unroll
;     for (int d = -1; d <= 1; ++d) {
;       int ss = s + d;
;       if (ss >= 0 && ss < 4096) {
;         u32x4 a = ldg16(HY + (size_t)ss * 1536 + c);
;         float wa[8]; ld8f(p.c_short + (d + 1) * 1536 + c, wa);
; #pragma unroll
;         for (int q = 0; q < 4; ++q) { x0[2 * q] += wa[2 * q] * bflo(a[q]); x0[2 * q + 1] += wa[2 * q + 1] * bfhi(a[q]); }
;       }
;     }
;     u32x4 y = *(const u32x4*)(sT + row * 72 + ck * 8);
;     float v[8];
; #pragma unroll
;     for (int q = 0; q < 4; ++q) { v[2 * q] = bflo(y[q]) * x0[2 * q]; v[2 * q + 1] = bfhi(y[q]) * x0[2 * q + 1]; }
;     store8(CD + ((size_t)b * 4096 + s) * 1024 + 512 + c, v);
;   }
	ds_read_b128 v[120:123], v118
	ds_read_b128 v[124:127], v118 offset:4608
	v_cndmask_b32_e64 v8, 0, v8, s[40:41]
	v_cndmask_b32_e64 v9, 0, v9, s[40:41]
	v_cndmask_b32_e64 v10, 0, v10, s[40:41]
	v_cndmask_b32_e64 v11, 0, v11, s[40:41]
	s_waitcnt lgkmcnt(1)
	v_lshlrev_b32_e32 v128, 16, v8
	v_and_b32_e32 v129, 0xffff0000, v8
	v_lshlrev_b32_e32 v130, 16, v12
	v_and_b32_e32 v131, 0xffff0000, v12
	v_lshlrev_b32_e32 v132, 16, v16
	v_and_b32_e32 v133, 0xffff0000, v16
	v_lshlrev_b32_e32 v134, 16, v120
	v_and_b32_e32 v135, 0xffff0000, v120
	v_pk_fma_f32 v[136:137], v[64:65], v[128:129], 0 op_sel_hi:[1,1,0]
	v_pk_fma_f32 v[136:137], v[72:73], v[130:131], v[136:137]
	v_pk_fma_f32 v[136:137], v[80:81], v[132:133], v[136:137]
	v_pk_mul_f32 v[136:137], v[134:135], v[136:137]
	v_cvt_pk_bf16_f32 v140, v136, v137
	v_lshlrev_b32_e32 v128, 16, v9
	v_and_b32_e32 v129, 0xffff0000, v9
	v_lshlrev_b32_e32 v130, 16, v13
	v_and_b32_e32 v131, 0xffff0000, v13
	v_lshlrev_b32_e32 v132, 16, v17
	v_and_b32_e32 v133, 0xffff0000, v17
	v_lshlrev_b32_e32 v134, 16, v121
	v_and_b32_e32 v135, 0xffff0000, v121
	v_pk_fma_f32 v[136:137], v[66:67], v[128:129], 0 op_sel_hi:[1,1,0]
	v_pk_fma_f32 v[136:137], v[74:75], v[130:131], v[136:137]
	v_pk_fma_f32 v[136:137], v[82:83], v[132:133], v[136:137]
	v_pk_mul_f32 v[136:137], v[134:135], v[136:137]
	v_cvt_pk_bf16_f32 v141, v136, v137
	v_lshlrev_b32_e32 v128, 16, v10
	v_and_b32_e32 v129, 0xffff0000, v10
	v_lshlrev_b32_e32 v130, 16, v14
	v_and_b32_e32 v131, 0xffff0000, v14
	v_lshlrev_b32_e32 v132, 16, v18
	v_and_b32_e32 v133, 0xffff0000, v18
	v_lshlrev_b32_e32 v134, 16, v122
	v_and_b32_e32 v135, 0xffff0000, v122
	v_pk_fma_f32 v[136:137], v[68:69], v[128:129], 0 op_sel_hi:[1,1,0]
	v_pk_fma_f32 v[136:137], v[76:77], v[130:131], v[136:137]
	v_pk_fma_f32 v[136:137], v[84:85], v[132:133], v[136:137]
	v_pk_mul_f32 v[136:137], v[134:135], v[136:137]
	v_cvt_pk_bf16_f32 v142, v136, v137
	v_lshlrev_b32_e32 v128, 16, v11
	v_and_b32_e32 v129, 0xffff0000, v11
	v_lshlrev_b32_e32 v130, 16, v15
	v_and_b32_e32 v131, 0xffff0000, v15
	v_lshlrev_b32_e32 v132, 16, v19
	v_and_b32_e32 v133, 0xffff0000, v19
	v_lshlrev_b32_e32 v134, 16, v123
	v_and_b32_e32 v135, 0xffff0000, v123
	v_pk_fma_f32 v[136:137], v[70:71], v[128:129], 0 op_sel_hi:[1,1,0]
	v_pk_fma_f32 v[136:137], v[78:79], v[130:131], v[136:137]
	v_pk_fma_f32 v[136:137], v[86:87], v[132:133], v[136:137]
	v_pk_mul_f32 v[136:137], v[134:135], v[136:137]
	v_cvt_pk_bf16_f32 v143, v136, v137
	global_store_dwordx4 v[96:97], v[140:143], off
	v_cndmask_b32_e64 v28, 0, v28, s[42:43]
	v_cndmask_b32_e64 v29, 0, v29, s[42:43]
	v_cndmask_b32_e64 v30, 0, v30, s[42:43]
	v_cndmask_b32_e64 v31, 0, v31, s[42:43]
	s_waitcnt lgkmcnt(0)
	v_lshlrev_b32_e32 v128, 16, v20
	v_and_b32_e32 v129, 0xffff0000, v20
	v_lshlrev_b32_e32 v130, 16, v24
	v_and_b32_e32 v131, 0xffff0000, v24
	v_lshlrev_b32_e32 v132, 16, v28
	v_and_b32_e32 v133, 0xffff0000, v28
	v_lshlrev_b32_e32 v134, 16, v124
	v_and_b32_e32 v135, 0xffff0000, v124
	v_pk_fma_f32 v[136:137], v[64:65], v[128:129], 0 op_sel_hi:[1,1,0]
	v_pk_fma_f32 v[136:137], v[72:73], v[130:131], v[136:137]
	v_pk_fma_f32 v[136:137], v[80:81], v[132:133], v[136:137]
	v_pk_mul_f32 v[136:137], v[134:135], v[136:137]
	v_cvt_pk_bf16_f32 v144, v136, v137
	v_lshlrev_b32_e32 v128, 16, v21
	v_and_b32_e32 v129, 0xffff0000, v21
	v_lshlrev_b32_e32 v130, 16, v25
	v_and_b32_e32 v131, 0xffff0000, v25
	v_lshlrev_b32_e32 v132, 16, v29
	v_and_b32_e32 v133, 0xffff0000, v29
	v_lshlrev_b32_e32 v134, 16, v125
	v_and_b32_e32 v135, 0xffff0000, v125
	v_pk_fma_f32 v[136:137], v[66:67], v[128:129], 0 op_sel_hi:[1,1,0]
	v_pk_fma_f32 v[136:137], v[74:75], v[130:131], v[136:137]
	v_pk_fma_f32 v[136:137], v[82:83], v[132:133], v[136:137]
	v_pk_mul_f32 v[136:137], v[134:135], v[136:137]
	v_cvt_pk_bf16_f32 v145, v136, v137
	v_lshlrev_b32_e32 v128, 16, v22
	v_and_b32_e32 v129, 0xffff0000, v22
	v_lshlrev_b32_e32 v130, 16, v26
	v_and_b32_e32 v131, 0xffff0000, v26
	v_lshlrev_b32_e32 v132, 16, v30
	v_and_b32_e32 v133, 0xffff0000, v30
	v_lshlrev_b32_e32 v134, 16, v126
	v_and_b32_e32 v135, 0xffff0000, v126
	v_pk_fma_f32 v[136:137], v[68:69], v[128:129], 0 op_sel_hi:[1,1,0]
	v_pk_fma_f32 v[136:137], v[76:77], v[130:131], v[136:137]
	v_pk_fma_f32 v[136:137], v[84:85], v[132:133], v[136:137]
	v_pk_mul_f32 v[136:137], v[134:135], v[136:137]
	v_cvt_pk_bf16_f32 v146, v136, v137
	v_lshlrev_b32_e32 v128, 16, v23
	v_and_b32_e32 v129, 0xffff0000, v23
	v_lshlrev_b32_e32 v130, 16, v27
	v_and_b32_e32 v131, 0xffff0000, v27
	v_lshlrev_b32_e32 v132, 16, v31
	v_and_b32_e32 v133, 0xffff0000, v31
	v_lshlrev_b32_e32 v134, 16, v127
	v_and_b32_e32 v135, 0xffff0000, v127
	v_pk_fma_f32 v[136:137], v[70:71], v[128:129], 0 op_sel_hi:[1,1,0]
	v_pk_fma_f32 v[136:137], v[78:79], v[130:131], v[136:137]
	v_pk_fma_f32 v[136:137], v[86:87], v[132:133], v[136:137]
	v_pk_mul_f32 v[136:137], v[134:135], v[136:137]
	v_cvt_pk_bf16_f32 v147, v136, v137
	global_store_dwordx4 v[98:99], v[144:147], off
	v_lshl_add_u64 v[96:97], v[96:97], 0, s[48:49]
	v_lshl_add_u64 v[98:99], v[98:99], 0, s[48:49]
	s_waitcnt vmcnt(2)
	ds_write_b16 v117, v32 offset:9216
	ds_write_b16_d16_hi v117, v32 offset:9360
	ds_write_b16 v117, v33 offset:9504
	ds_write_b16_d16_hi v117, v33 offset:9648
	ds_write_b16 v117, v34 offset:9792
	ds_write_b16_d16_hi v117, v34 offset:9936
	ds_write_b16 v117, v35 offset:10080
	ds_write_b16_d16_hi v117, v35 offset:10224
	ds_write_b16 v117, v36 offset:9280
	ds_write_b16_d16_hi v117, v36 offset:9424
	ds_write_b16 v117, v37 offset:9568
	ds_write_b16_d16_hi v117, v37 offset:9712
	ds_write_b16 v117, v38 offset:9856
	ds_write_b16_d16_hi v117, v38 offset:10000
	ds_write_b16 v117, v39 offset:10144
	ds_write_b16_d16_hi v117, v39 offset:10288
	s_waitcnt lgkmcnt(0)
	s_barrier
; DI float bflo(unsigned u) { return __uint_as_float(u << 16); }
; DI float bfhi(unsigned u) { return __uint_as_float(u & 0xffff0000u); }
; DI void hyena_post_tile(const Params& p, int item, char* smem) {
;     ...
;   bf16_t* CD = (bf16_t*)(p.ws + OFF_AB);
; #pragma unroll
;   for (int i = 0; i < 2; ++i) {
;     int row = (tid >> 3) + 32 * i, ck = tid & 7, s = st * 64 + row, c = ct * 64 + ck * 8;
;     float x0[8];
; #pragma unroll
;     for (int j = 0; j < 8; ++j) x0[j] = 0.f;
; #pragma unroll
;     for (int d = -1; d <= 1; ++d) {
;       int ss = s + d;
;       if (ss >= 0 && ss < 4096) {
;         u32x4 a = ldg16(HY + (size_t)ss * 1536 + c);
;         float wa[8]; ld8f(p.c_short + (d + 1) * 1536 + c, wa);
; #pragma unroll
;         for (int q = 0; q < 4; ++q) { x0[2 * q] += wa[2 * q] * bflo(a[q]); x0[2 * q + 1] += wa[2 * q + 1] * bfhi(a[q]); }
;       }
;     }
;     u32x4 y = *(const u32x4*)(sT + row * 72 + ck * 8);
;     float v[8];
; #pragma unroll
;     for (int q = 0; q < 4; ++q) { v[2 * q] = bflo(y[q]) * x0[2 * q]; v[2 * q + 1] = bfhi(y[q]) * x0[2 * q + 1]; }
;     store8(CD + ((size_t)b * 4096 + s) * 1024 + 512 + c, v);
;   }
	ds_read_b128 v[120:123], v118 offset:9216
	ds_read_b128 v[124:127], v118 offset:13824
	v_cndmask_b32_e64 v40, 0, v40, s[40:41]
	v_cndmask_b32_e64 v41, 0, v41, s[40:41]
	v_cndmask_b32_e64 v42, 0, v42, s[40:41]
	v_cndmask_b32_e64 v43, 0, v43, s[40:41]
	s_waitcnt lgkmcnt(1)
	v_lshlrev_b32_e32 v128, 16, v40
	v_and_b32_e32 v129, 0xffff0000, v40
	v_lshlrev_b32_e32 v130, 16, v44
	v_and_b32_e32 v131, 0xffff0000, v44
	v_lshlrev_b32_e32 v132, 16, v48
	v_and_b32_e32 v133, 0xffff0000, v48
	v_lshlrev_b32_e32 v134, 16, v120
	v_and_b32_e32 v135, 0xffff0000, v120
	v_pk_fma_f32 v[136:137], v[64:65], v[128:129], 0 op_sel_hi:[1,1,0]
	v_pk_fma_f32 v[136:137], v[72:73], v[130:131], v[136:137]
	v_pk_fma_f32 v[136:137], v[80:81], v[132:133], v[136:137]
	v_pk_mul_f32 v[136:137], v[134:135], v[136:137]
	v_cvt_pk_bf16_f32 v140, v136, v137
	v_lshlrev_b32_e32 v128, 16, v41
	v_and_b32_e32 v129, 0xffff0000, v41
	v_lshlrev_b32_e32 v130, 16, v45
	v_and_b32_e32 v131, 0xffff0000, v45
	v_lshlrev_b32_e32 v132, 16, v49
	v_and_b32_e32 v133, 0xffff0000, v49
	v_lshlrev_b32_e32 v134, 16, v121
	v_and_b32_e32 v135, 0xffff0000, v121
	v_pk_fma_f32 v[136:137], v[66:67], v[128:129], 0 op_sel_hi:[1,1,0]
	v_pk_fma_f32 v[136:137], v[74:75], v[130:131], v[136:137]
	v_pk_fma_f32 v[136:137], v[82:83], v[132:133], v[136:137]
	v_pk_mul_f32 v[136:137], v[134:135], v[136:137]
	v_cvt_pk_bf16_f32 v141, v136, v137
	v_lshlrev_b32_e32 v128, 16, v42
	v_and_b32_e32 v129, 0xffff0000, v42
	v_lshlrev_b32_e32 v130, 16, v46
	v_and_b32_e32 v131, 0xffff0000, v46
	v_lshlrev_b32_e32 v132, 16, v50
	v_and_b32_e32 v133, 0xffff0000, v50
	v_lshlrev_b32_e32 v134, 16, v122
	v_and_b32_e32 v135, 0xffff0000, v122
	v_pk_fma_f32 v[136:137], v[68:69], v[128:129], 0 op_sel_hi:[1,1,0]
	v_pk_fma_f32 v[136:137], v[76:77], v[130:131], v[136:137]
	v_pk_fma_f32 v[136:137], v[84:85], v[132:133], v[136:137]
	v_pk_mul_f32 v[136:137], v[134:135], v[136:137]
	v_cvt_pk_bf16_f32 v142, v136, v137
	v_lshlrev_b32_e32 v128, 16, v43
	v_and_b32_e32 v129, 0xffff0000, v43
	v_lshlrev_b32_e32 v130, 16, v47
	v_and_b32_e32 v131, 0xffff0000, v47
	v_lshlrev_b32_e32 v132, 16, v51
	v_and_b32_e32 v133, 0xffff0000, v51
	v_lshlrev_b32_e32 v134, 16, v123
	v_and_b32_e32 v135, 0xffff0000, v123
	v_pk_fma_f32 v[136:137], v[70:71], v[128:129], 0 op_sel_hi:[1,1,0]
	v_pk_fma_f32 v[136:137], v[78:79], v[130:131], v[136:137]
	v_pk_fma_f32 v[136:137], v[86:87], v[132:133], v[136:137]
	v_pk_mul_f32 v[136:137], v[134:135], v[136:137]
	v_cvt_pk_bf16_f32 v143, v136, v137
	global_store_dwordx4 v[96:97], v[140:143], off
	v_cndmask_b32_e64 v60, 0, v60, s[42:43]
	v_cndmask_b32_e64 v61, 0, v61, s[42:43]
	v_cndmask_b32_e64 v62, 0, v62, s[42:43]
	v_cndmask_b32_e64 v63, 0, v63, s[42:43]
	s_waitcnt lgkmcnt(0)
	v_lshlrev_b32_e32 v128, 16, v52
	v_and_b32_e32 v129, 0xffff0000, v52
	v_lshlrev_b32_e32 v130, 16, v56
	v_and_b32_e32 v131, 0xffff0000, v56
	v_lshlrev_b32_e32 v132, 16, v60
	v_and_b32_e32 v133, 0xffff0000, v60
	v_lshlrev_b32_e32 v134, 16, v124
	v_and_b32_e32 v135, 0xffff0000, v124
	v_pk_fma_f32 v[136:137], v[64:65], v[128:129], 0 op_sel_hi:[1,1,0]
	v_pk_fma_f32 v[136:137], v[72:73], v[130:131], v[136:137]
	v_pk_fma_f32 v[136:137], v[80:81], v[132:133], v[136:137]
	v_pk_mul_f32 v[136:137], v[134:135], v[136:137]
	v_cvt_pk_bf16_f32 v144, v136, v137
	v_lshlrev_b32_e32 v128, 16, v53
	v_and_b32_e32 v129, 0xffff0000, v53
	v_lshlrev_b32_e32 v130, 16, v57
	v_and_b32_e32 v131, 0xffff0000, v57
	v_lshlrev_b32_e32 v132, 16, v61
	v_and_b32_e32 v133, 0xffff0000, v61
	v_lshlrev_b32_e32 v134, 16, v125
	v_and_b32_e32 v135, 0xffff0000, v125
	v_pk_fma_f32 v[136:137], v[66:67], v[128:129], 0 op_sel_hi:[1,1,0]
	v_pk_fma_f32 v[136:137], v[74:75], v[130:131], v[136:137]
	v_pk_fma_f32 v[136:137], v[82:83], v[132:133], v[136:137]
	v_pk_mul_f32 v[136:137], v[134:135], v[136:137]
	v_cvt_pk_bf16_f32 v145, v136, v137
	v_lshlrev_b32_e32 v128, 16, v54
	v_and_b32_e32 v129, 0xffff0000, v54
	v_lshlrev_b32_e32 v130, 16, v58
	v_and_b32_e32 v131, 0xffff0000, v58
	v_lshlrev_b32_e32 v132, 16, v62
	v_and_b32_e32 v133, 0xffff0000, v62
	v_lshlrev_b32_e32 v134, 16, v126
	v_and_b32_e32 v135, 0xffff0000, v126
	v_pk_fma_f32 v[136:137], v[68:69], v[128:129], 0 op_sel_hi:[1,1,0]
	v_pk_fma_f32 v[136:137], v[76:77], v[130:131], v[136:137]
	v_pk_fma_f32 v[136:137], v[84:85], v[132:133], v[136:137]
	v_pk_mul_f32 v[136:137], v[134:135], v[136:137]
	v_cvt_pk_bf16_f32 v146, v136, v137
	v_lshlrev_b32_e32 v128, 16, v55
	v_and_b32_e32 v129, 0xffff0000, v55
	v_lshlrev_b32_e32 v130, 16, v59
	v_and_b32_e32 v131, 0xffff0000, v59
	v_lshlrev_b32_e32 v132, 16, v63
	v_and_b32_e32 v133, 0xffff0000, v63
	v_lshlrev_b32_e32 v134, 16, v127
	v_and_b32_e32 v135, 0xffff0000, v127
	v_pk_fma_f32 v[136:137], v[70:71], v[128:129], 0 op_sel_hi:[1,1,0]
	v_pk_fma_f32 v[136:137], v[78:79], v[130:131], v[136:137]
	v_pk_fma_f32 v[136:137], v[86:87], v[132:133], v[136:137]
	v_pk_mul_f32 v[136:137], v[134:135], v[136:137]
	v_cvt_pk_bf16_f32 v147, v136, v137
	global_store_dwordx4 v[98:99], v[144:147], off
	v_lshl_add_u64 v[96:97], v[96:97], 0, s[48:49]
	v_lshl_add_u64 v[98:99], v[98:99], 0, s[48:49]
	s_branch .LBB0_997
; DI float bflo(unsigned u) { return __uint_as_float(u << 16); }
; DI float bfhi(unsigned u) { return __uint_as_float(u & 0xffff0000u); }
; DI int tidx() { return tid512() & 255; }
; DI void hyena_post_tile(const Params& p, int item, char* smem) {
;   const int tid = tidx();
;   const int ct = item & 7, st = (item >> 3) & 63, b = item >> 9;
;   const bf16_t* HY = (const bf16_t*)(p.ws + OFF_HY) + (size_t)b * 4096 * 1536;
;   const bf16_t* yT = (const bf16_t*)(p.hbuf + HB_YT);
;   bf16_t* sT = (bf16_t*)smem;
;   __syncthreads();
; #pragma unroll
;   for (int i = 0; i < 2; ++i) {
;     int row = (tid >> 3) + 32 * i, ck = tid & 7;
;     u32x4 u = ldg16(yT + ((size_t)(ct * 64 + row) * 8 + b) * 4096 + st * 64 + ck * 8);
; #pragma unroll
;     for (int j = 0; j < 8; ++j) { unsigned wv = u[j >> 1]; sT[(ck * 8 + j) * 72 + row] = (bf16_t)((j & 1) ? (wv >> 16) : (wv & 0xffffu)); }
;   }
;   __syncthreads();
;   bf16_t* CD = (bf16_t*)(p.ws + OFF_AB);
; #pragma unroll
;   for (int i = 0; i < 2; ++i) {
;     int row = (tid >> 3) + 32 * i, ck = tid & 7, s = st * 64 + row, c = ct * 64 + ck * 8;
;     float x0[8];
; #pragma unroll
;     for (int j = 0; j < 8; ++j) x0[j] = 0.f;
; #pragma unroll
;     for (int d = -1; d <= 1; ++d) {
;       int ss = s + d;
;       if (ss >= 0 && ss < 4096) {
;         u32x4 a = ldg16(HY + (size_t)ss * 1536 + c);
;         float wa[8]; ld8f(p.c_short + (d + 1) * 1536 + c, wa);
; #pragma unroll
;         for (int q = 0; q < 4; ++q) { x0[2 * q] += wa[2 * q] * bflo(a[q]); x0[2 * q + 1] += wa[2 * q + 1] * bfhi(a[q]); }
;       }
;     }
;     u32x4 y = *(const u32x4*)(sT + row * 72 + ck * 8);
;     float v[8];
; #pragma unroll
;     for (int q = 0; q < 4; ++q) { v[2 * q] = bflo(y[q]) * x0[2 * q]; v[2 * q + 1] = bfhi(y[q]) * x0[2 * q + 1]; }
.Lpost_fallback:
	s_add_i32 s1, s0, 0xfffffc00
	v_mov_b32_e32 v0, v196
	s_lshr_b32 s4, s1, 9
	s_lshl_b32 s1, s1, 3
	s_and_b32 s1, s1, 0xfc0
	s_and_b32 s22, s0, 7
	v_bfe_u32 v14, v0, 3, 5
	s_lshl_b32 s2, s1, 1
	v_lshlrev_b32_e32 v0, 3, v0
	s_add_u32 s2, s25, s2
	v_and_b32_e32 v15, 56, v0
	s_addc_u32 s3, s26, 0
	v_lshlrev_b32_e32 v128, 1, v15
	v_lshl_add_u64 v[0:1], s[2:3], 0, v[128:129]
	s_lshl_b32 s2, s22, 21
	s_lshl_b32 s3, s4, 12
	v_lshlrev_b32_e32 v2, 15, v14
	s_add_i32 s3, s3, s2
	v_add_lshl_u32 v128, v2, s3, 1
	v_lshl_add_u64 v[2:3], v[0:1], 0, v[128:129]
	s_barrier
	global_load_dwordx4 v[20:23], v[2:3], off
	v_or_b32_e32 v16, 32, v14
	v_lshlrev_b32_e32 v2, 15, v16
	v_add_lshl_u32 v128, v2, s3, 1
	v_lshl_add_u64 v[0:1], v[0:1], 0, v[128:129]
	global_load_dwordx4 v[24:27], v[0:1], off
	s_mul_i32 s2, s4, 0xc00000
	v_mov_b32_e32 v0, s24
	s_mul_hi_u32 s3, s4, 0xc00000
	v_or_b32_e32 v17, s1, v14
	v_lshl_or_b32 v9, s22, 6, v15
	v_readlane_b32 s52, v247, 34
	s_add_u32 s2, s14, s2
	v_mov_b32_e32 v1, v129
	v_mov_b32_e32 v4, 0
	v_mad_u32_u24 v18, v15, s30, v0
	v_add_u32_e32 v10, -1, v17
	v_lshlrev_b32_e32 v0, 2, v9
	v_readlane_b32 s58, v247, 40
	v_readlane_b32 s59, v247, 41
	s_addc_u32 s3, s15, s3
	v_lshlrev_b32_e32 v128, 1, v9
	v_mov_b32_e32 v5, v4
	v_mov_b32_e32 v2, v4
	v_mov_b32_e32 v3, v4
	v_mov_b32_e32 v6, v4
	v_mov_b32_e32 v7, v4
	v_mov_b32_e32 v8, v4
	v_lshl_add_u32 v11, v14, 1, v18
	v_cmp_gt_u32_e32 vcc, s31, v10
	v_lshl_add_u64 v[0:1], s[58:59], 0, v[0:1]
	v_lshl_add_u64 v[12:13], s[2:3], 0, v[128:129]
	v_mov_b32_e32 v9, v4
	v_readlane_b32 s53, v247, 35
	v_readlane_b32 s54, v247, 36
	v_readlane_b32 s55, v247, 37
	v_readlane_b32 s56, v247, 38
	v_readlane_b32 s57, v247, 39
	v_readlane_b32 s60, v247, 42
	v_readlane_b32 s61, v247, 43
	v_readlane_b32 s62, v247, 44
	v_readlane_b32 s63, v247, 45
	v_readlane_b32 s64, v247, 46
	v_readlane_b32 s65, v247, 47
	v_readlane_b32 s66, v247, 48
	v_readlane_b32 s67, v247, 49
	s_waitcnt vmcnt(1)
	ds_write_b16 v11, v20
	ds_write_b16_d16_hi v11, v20 offset:144
	ds_write_b16 v11, v21 offset:288
	ds_write_b16_d16_hi v11, v21 offset:432
	ds_write_b16 v11, v22 offset:576
	ds_write_b16_d16_hi v11, v22 offset:720
	ds_write_b16 v11, v23 offset:864
	ds_write_b16_d16_hi v11, v23 offset:1008
	s_waitcnt vmcnt(0)
	ds_write_b16 v11, v24 offset:64
	ds_write_b16_d16_hi v11, v24 offset:208
	ds_write_b16 v11, v25 offset:352
	ds_write_b16_d16_hi v11, v25 offset:496
	ds_write_b16 v11, v26 offset:640
	ds_write_b16_d16_hi v11, v26 offset:784
	ds_write_b16 v11, v27 offset:928
	ds_write_b16_d16_hi v11, v27 offset:1072
	s_waitcnt lgkmcnt(0)
	s_barrier
	s_and_saveexec_b64 s[2:3], vcc
	s_cbranch_execz .LBB0_990
	v_mul_i32_i24_e32 v2, 0x600, v10
	v_mov_b32_e32 v3, v129
	v_lshl_add_u64 v[2:3], v[2:3], 1, v[12:13]
	global_load_dwordx4 v[2:5], v[2:3], off
	s_nop 0
	global_load_dwordx4 v[6:9], v[0:1], off
	global_load_dwordx4 v[20:23], v[0:1], off offset:16
	s_waitcnt vmcnt(2)
	v_lshlrev_b32_e32 v10, 16, v2
	v_and_b32_e32 v11, 0xffff0000, v2
	v_lshlrev_b32_e32 v24, 16, v3
	v_and_b32_e32 v25, 0xffff0000, v3
	v_lshlrev_b32_e32 v26, 16, v4
	v_and_b32_e32 v27, 0xffff0000, v4
	v_lshlrev_b32_e32 v4, 16, v5
	v_and_b32_e32 v5, 0xffff0000, v5
	s_waitcnt vmcnt(1)
	v_pk_fma_f32 v[2:3], v[6:7], v[10:11], 0 op_sel_hi:[1,1,0]
	v_pk_fma_f32 v[6:7], v[8:9], v[24:25], 0 op_sel_hi:[1,1,0]
	s_waitcnt vmcnt(0)
	v_pk_fma_f32 v[8:9], v[20:21], v[26:27], 0 op_sel_hi:[1,1,0]
	v_pk_fma_f32 v[4:5], v[22:23], v[4:5], 0 op_sel_hi:[1,1,0]
